# relaxed K-loop DMA waits: per-half-tile vmcnt(10) one phase before first read in all 5 GEMM K-loops (was one vmcnt(6) per K-tile)
# baseline (speedup 1.0000x reference)
.LBB0_150:
	s_add_u32 s45, s6, 0xfffc0080
	s_addc_u32 s47, s7, -1
	s_add_i32 s55, 0, 0x10000
	v_add_u32_e32 v0, s55, v152
	ds_read_b128 v[142:145], v0
	ds_read_b128 v[146:149], v0 offset:1024
	ds_read_b128 v[154:157], v0 offset:2048
	ds_read_b128 v[158:161], v0 offset:3072
	s_cmp_eq_u32 s44, 12
	s_cselect_b32 s89, s5, s47
	s_cselect_b32 s88, s13, s45
	s_cselect_b32 s87, s11, s34
	s_cselect_b32 s86, s22, s23
	v_lshl_add_u64 v[150:151], s[6:7], 0, v[138:139]
	s_add_i32 m0, s9, 0xc000
	ds_read_b128 v[162:165], v153
	ds_read_b128 v[166:169], v153 offset:1024
	ds_read_b128 v[170:173], v153 offset:2048
	ds_read_b128 v[174:177], v153 offset:3072
	ds_read_b128 v[178:181], v153 offset:4096
	ds_read_b128 v[182:185], v153 offset:5120
	ds_read_b128 v[190:193], v153 offset:6144
	ds_read_b128 v[194:197], v153 offset:7168
	global_load_lds_dwordx4 v[150:151], off
	v_lshl_add_u64 v[150:151], s[6:7], 0, v[140:141]
	s_add_i32 m0, s9, 0xe000
	s_nop 0
	global_load_lds_dwordx4 v[150:151], off
	s_waitcnt lgkmcnt(8)
	s_waitcnt vmcnt(10)
	s_barrier
	s_waitcnt lgkmcnt(0)
	s_setprio 1
	s_waitcnt lgkmcnt(0)
	v_mfma_f32_16x16x32_bf16 v[126:129], v[142:145], v[162:165], v[126:129]
	v_mfma_f32_16x16x32_bf16 v[122:125], v[154:157], v[162:165], v[122:125]
	v_mfma_f32_16x16x32_bf16 v[110:113], v[142:145], v[170:173], v[110:113]
	v_mfma_f32_16x16x32_bf16 v[106:109], v[154:157], v[170:173], v[106:109]
	v_mfma_f32_16x16x32_bf16 v[94:97], v[142:145], v[178:181], v[94:97]
	v_mfma_f32_16x16x32_bf16 v[90:93], v[154:157], v[178:181], v[90:93]
	v_mfma_f32_16x16x32_bf16 v[78:81], v[142:145], v[190:193], v[78:81]
	v_mfma_f32_16x16x32_bf16 v[74:77], v[154:157], v[190:193], v[74:77]
	v_mfma_f32_16x16x32_bf16 v[126:129], v[146:149], v[166:169], v[126:129]
	v_mfma_f32_16x16x32_bf16 v[122:125], v[158:161], v[166:169], v[122:125]
	v_mfma_f32_16x16x32_bf16 v[110:113], v[146:149], v[174:177], v[110:113]
	v_mfma_f32_16x16x32_bf16 v[106:109], v[158:161], v[174:177], v[106:109]
	v_mfma_f32_16x16x32_bf16 v[94:97], v[146:149], v[182:185], v[94:97]
	v_mfma_f32_16x16x32_bf16 v[90:93], v[158:161], v[182:185], v[90:93]
	v_mfma_f32_16x16x32_bf16 v[78:81], v[146:149], v[194:197], v[78:81]
	v_mfma_f32_16x16x32_bf16 v[74:77], v[158:161], v[194:197], v[74:77]
	s_setprio 0
	s_barrier
	s_add_i32 s45, 0, 0x14000
	s_add_i32 s47, s55, s36
	v_add_u32_e32 v0, s45, v152
	v_lshl_add_u64 v[150:151], s[86:87], 0, v[132:133]
	s_mov_b32 m0, s47
	ds_read_b128 v[198:201], v0
	ds_read_b128 v[202:205], v0 offset:1024
	ds_read_b128 v[206:209], v0 offset:2048
	ds_read_b128 v[210:213], v0 offset:3072
	global_load_lds_dwordx4 v[150:151], off
	v_lshl_add_u64 v[186:187], s[86:87], 0, v[136:137]
	s_add_i32 m0, s47, 0x2000
	s_nop 0
	global_load_lds_dwordx4 v[186:187], off
	s_waitcnt vmcnt(10)
	s_barrier
	s_waitcnt lgkmcnt(0)
	s_setprio 1
	s_waitcnt lgkmcnt(0)
	v_mfma_f32_16x16x32_bf16 v[118:121], v[198:201], v[162:165], v[118:121]
	v_mfma_f32_16x16x32_bf16 v[114:117], v[206:209], v[162:165], v[114:117]
	v_mfma_f32_16x16x32_bf16 v[102:105], v[198:201], v[170:173], v[102:105]
	v_mfma_f32_16x16x32_bf16 v[98:101], v[206:209], v[170:173], v[98:101]
	v_mfma_f32_16x16x32_bf16 v[86:89], v[198:201], v[178:181], v[86:89]
	v_mfma_f32_16x16x32_bf16 v[82:85], v[206:209], v[178:181], v[82:85]
	v_mfma_f32_16x16x32_bf16 v[70:73], v[198:201], v[190:193], v[70:73]
	v_mfma_f32_16x16x32_bf16 v[66:69], v[206:209], v[190:193], v[66:69]
	v_mfma_f32_16x16x32_bf16 v[118:121], v[202:205], v[166:169], v[118:121]
	v_mfma_f32_16x16x32_bf16 v[114:117], v[210:213], v[166:169], v[114:117]
	v_mfma_f32_16x16x32_bf16 v[102:105], v[202:205], v[174:177], v[102:105]
	v_mfma_f32_16x16x32_bf16 v[98:101], v[210:213], v[174:177], v[98:101]
	v_mfma_f32_16x16x32_bf16 v[86:89], v[202:205], v[182:185], v[86:89]
	v_mfma_f32_16x16x32_bf16 v[82:85], v[210:213], v[182:185], v[82:85]
	v_mfma_f32_16x16x32_bf16 v[70:73], v[202:205], v[194:197], v[70:73]
	v_mfma_f32_16x16x32_bf16 v[66:69], v[210:213], v[194:197], v[66:69]
	s_setprio 0
	s_mov_b32 m0, s9
	v_lshl_add_u64 v[214:215], s[88:89], 0, v[130:131]
	s_barrier
	ds_read_b128 v[162:165], v153 offset:16384
	ds_read_b128 v[166:169], v153 offset:17408
	ds_read_b128 v[170:173], v153 offset:18432
	ds_read_b128 v[174:177], v153 offset:19456
	ds_read_b128 v[178:181], v153 offset:20480
	ds_read_b128 v[182:185], v153 offset:21504
	ds_read_b128 v[190:193], v153 offset:22528
	ds_read_b128 v[194:197], v153 offset:23552
	global_load_lds_dwordx4 v[214:215], off
	v_lshl_add_u64 v[216:217], s[88:89], 0, v[134:135]
	s_mov_b32 m0, s37
	s_nop 0
	global_load_lds_dwordx4 v[216:217], off
	s_barrier
	s_waitcnt lgkmcnt(0)
	s_setprio 1
	s_waitcnt lgkmcnt(0)
	v_mfma_f32_16x16x32_bf16 v[62:65], v[142:145], v[162:165], v[62:65]
	v_mfma_f32_16x16x32_bf16 v[58:61], v[154:157], v[162:165], v[58:61]
	v_mfma_f32_16x16x32_bf16 v[46:49], v[142:145], v[170:173], v[46:49]
	v_mfma_f32_16x16x32_bf16 v[42:45], v[154:157], v[170:173], v[42:45]
	v_mfma_f32_16x16x32_bf16 v[30:33], v[142:145], v[178:181], v[30:33]
	v_mfma_f32_16x16x32_bf16 v[26:29], v[154:157], v[178:181], v[26:29]
	v_mfma_f32_16x16x32_bf16 v[14:17], v[142:145], v[190:193], v[14:17]
	v_mfma_f32_16x16x32_bf16 v[10:13], v[154:157], v[190:193], v[10:13]
	v_mfma_f32_16x16x32_bf16 v[62:65], v[146:149], v[166:169], v[62:65]
	v_mfma_f32_16x16x32_bf16 v[58:61], v[158:161], v[166:169], v[58:61]
	v_mfma_f32_16x16x32_bf16 v[46:49], v[146:149], v[174:177], v[46:49]
	v_mfma_f32_16x16x32_bf16 v[42:45], v[158:161], v[174:177], v[42:45]
	v_mfma_f32_16x16x32_bf16 v[30:33], v[146:149], v[182:185], v[30:33]
	v_mfma_f32_16x16x32_bf16 v[26:29], v[158:161], v[182:185], v[26:29]
	v_mfma_f32_16x16x32_bf16 v[14:17], v[146:149], v[194:197], v[14:17]
	v_mfma_f32_16x16x32_bf16 v[10:13], v[158:161], v[194:197], v[10:13]
	s_setprio 0
	s_barrier
	s_add_u32 s78, s86, 0x40000
	s_addc_u32 s79, s87, 0
	s_add_i32 s45, s45, s36
	v_lshl_add_u64 v[142:143], s[78:79], 0, v[132:133]
	s_mov_b32 m0, s45
	s_nop 0
	global_load_lds_dwordx4 v[142:143], off
	v_lshl_add_u64 v[142:143], s[78:79], 0, v[136:137]
	s_add_i32 m0, s45, 0x2000
	s_nop 0
	global_load_lds_dwordx4 v[142:143], off
	s_waitcnt vmcnt(10)
	s_barrier
	s_setprio 1
	v_mfma_f32_16x16x32_bf16 v[54:57], v[198:201], v[162:165], v[54:57]
	v_mfma_f32_16x16x32_bf16 v[50:53], v[206:209], v[162:165], v[50:53]
	v_mfma_f32_16x16x32_bf16 v[38:41], v[198:201], v[170:173], v[38:41]
	v_mfma_f32_16x16x32_bf16 v[34:37], v[206:209], v[170:173], v[34:37]
	v_mfma_f32_16x16x32_bf16 v[22:25], v[198:201], v[178:181], v[22:25]
	v_mfma_f32_16x16x32_bf16 v[18:21], v[206:209], v[178:181], v[18:21]
	v_mfma_f32_16x16x32_bf16 v[6:9], v[198:201], v[190:193], v[6:9]
	v_mfma_f32_16x16x32_bf16 v[2:5], v[206:209], v[190:193], v[2:5]
	v_mfma_f32_16x16x32_bf16 v[54:57], v[202:205], v[166:169], v[54:57]
	v_mfma_f32_16x16x32_bf16 v[50:53], v[210:213], v[166:169], v[50:53]
	v_mfma_f32_16x16x32_bf16 v[38:41], v[202:205], v[174:177], v[38:41]
	v_mfma_f32_16x16x32_bf16 v[34:37], v[210:213], v[174:177], v[34:37]
	v_mfma_f32_16x16x32_bf16 v[22:25], v[202:205], v[182:185], v[22:25]
	v_mfma_f32_16x16x32_bf16 v[18:21], v[210:213], v[182:185], v[18:21]
	v_mfma_f32_16x16x32_bf16 v[6:9], v[202:205], v[194:197], v[6:9]
	v_mfma_f32_16x16x32_bf16 v[2:5], v[210:213], v[194:197], v[2:5]
	s_setprio 0
	s_add_i32 s45, 0, 0x18000
	v_add_u32_e32 v0, s45, v152
	s_barrier
	ds_read_b128 v[142:145], v0
	ds_read_b128 v[146:149], v0 offset:1024
	ds_read_b128 v[154:157], v0 offset:2048
	ds_read_b128 v[158:161], v0 offset:3072
	s_add_u32 s78, s88, 0x40000
	s_addc_u32 s79, s89, 0
	s_mov_b32 m0, s38
	v_lshl_add_u64 v[198:199], s[78:79], 0, v[130:131]
	ds_read_b128 v[162:165], v153 offset:32768
	ds_read_b128 v[166:169], v153 offset:33792
	ds_read_b128 v[170:173], v153 offset:34816
	ds_read_b128 v[174:177], v153 offset:35840
	ds_read_b128 v[178:181], v153 offset:36864
	ds_read_b128 v[182:185], v153 offset:37888
	ds_read_b128 v[190:193], v153 offset:38912
	ds_read_b128 v[194:197], v153 offset:39936
	global_load_lds_dwordx4 v[198:199], off
	v_lshl_add_u64 v[198:199], s[78:79], 0, v[134:135]
	s_mov_b32 m0, s39
	s_nop 0
	global_load_lds_dwordx4 v[198:199], off
	s_waitcnt lgkmcnt(8)
	s_waitcnt vmcnt(10)
	s_barrier
	s_waitcnt lgkmcnt(0)
	s_setprio 1
	s_waitcnt lgkmcnt(0)
	v_mfma_f32_16x16x32_bf16 v[126:129], v[142:145], v[162:165], v[126:129]
	v_mfma_f32_16x16x32_bf16 v[122:125], v[154:157], v[162:165], v[122:125]
	v_mfma_f32_16x16x32_bf16 v[110:113], v[142:145], v[170:173], v[110:113]
	v_mfma_f32_16x16x32_bf16 v[106:109], v[154:157], v[170:173], v[106:109]
	v_mfma_f32_16x16x32_bf16 v[94:97], v[142:145], v[178:181], v[94:97]
	v_mfma_f32_16x16x32_bf16 v[90:93], v[154:157], v[178:181], v[90:93]
	v_mfma_f32_16x16x32_bf16 v[78:81], v[142:145], v[190:193], v[78:81]
	v_mfma_f32_16x16x32_bf16 v[74:77], v[154:157], v[190:193], v[74:77]
	v_mfma_f32_16x16x32_bf16 v[126:129], v[146:149], v[166:169], v[126:129]
	v_mfma_f32_16x16x32_bf16 v[122:125], v[158:161], v[166:169], v[122:125]
	v_mfma_f32_16x16x32_bf16 v[110:113], v[146:149], v[174:177], v[110:113]
	v_mfma_f32_16x16x32_bf16 v[106:109], v[158:161], v[174:177], v[106:109]
	v_mfma_f32_16x16x32_bf16 v[94:97], v[146:149], v[182:185], v[94:97]
	v_mfma_f32_16x16x32_bf16 v[90:93], v[158:161], v[182:185], v[90:93]
	v_mfma_f32_16x16x32_bf16 v[78:81], v[146:149], v[194:197], v[78:81]
	v_mfma_f32_16x16x32_bf16 v[74:77], v[158:161], v[194:197], v[74:77]
	s_setprio 0
	s_barrier
	s_add_i32 s47, 0, 0x1c000
	s_add_i32 s45, s45, s36
	v_add_u32_e32 v0, s47, v152
	v_lshl_add_u64 v[150:151], v[150:151], 0, s[40:41]
	s_mov_b32 m0, s45
	ds_read_b128 v[198:201], v0
	ds_read_b128 v[202:205], v0 offset:1024
	ds_read_b128 v[206:209], v0 offset:2048
	ds_read_b128 v[210:213], v0 offset:3072
	global_load_lds_dwordx4 v[150:151], off
	v_lshl_add_u64 v[150:151], v[186:187], 0, s[40:41]
	s_add_i32 m0, s45, 0x2000
	s_nop 0
	global_load_lds_dwordx4 v[150:151], off
	s_waitcnt vmcnt(10)
	s_barrier
	s_waitcnt lgkmcnt(0)
	s_setprio 1
	s_waitcnt lgkmcnt(0)
	v_mfma_f32_16x16x32_bf16 v[118:121], v[198:201], v[162:165], v[118:121]
	v_mfma_f32_16x16x32_bf16 v[114:117], v[206:209], v[162:165], v[114:117]
	v_mfma_f32_16x16x32_bf16 v[102:105], v[198:201], v[170:173], v[102:105]
	v_mfma_f32_16x16x32_bf16 v[98:101], v[206:209], v[170:173], v[98:101]
	v_mfma_f32_16x16x32_bf16 v[86:89], v[198:201], v[178:181], v[86:89]
	v_mfma_f32_16x16x32_bf16 v[82:85], v[206:209], v[178:181], v[82:85]
	v_mfma_f32_16x16x32_bf16 v[70:73], v[198:201], v[190:193], v[70:73]
	v_mfma_f32_16x16x32_bf16 v[66:69], v[206:209], v[190:193], v[66:69]
	v_mfma_f32_16x16x32_bf16 v[118:121], v[202:205], v[166:169], v[118:121]
	v_mfma_f32_16x16x32_bf16 v[114:117], v[210:213], v[166:169], v[114:117]
	v_mfma_f32_16x16x32_bf16 v[102:105], v[202:205], v[174:177], v[102:105]
	v_mfma_f32_16x16x32_bf16 v[98:101], v[210:213], v[174:177], v[98:101]
	v_mfma_f32_16x16x32_bf16 v[86:89], v[202:205], v[182:185], v[86:89]
	v_mfma_f32_16x16x32_bf16 v[82:85], v[210:213], v[182:185], v[82:85]
	v_mfma_f32_16x16x32_bf16 v[70:73], v[202:205], v[194:197], v[70:73]
	v_mfma_f32_16x16x32_bf16 v[66:69], v[210:213], v[194:197], v[66:69]
	s_setprio 0
	s_mov_b32 m0, s60
	v_lshl_add_u64 v[150:151], v[214:215], 0, s[40:41]
	s_barrier
	ds_read_b128 v[162:165], v153 offset:49152
	ds_read_b128 v[166:169], v153 offset:50176
	ds_read_b128 v[170:173], v153 offset:51200
	ds_read_b128 v[174:177], v153 offset:52224
	ds_read_b128 v[178:181], v153 offset:53248
	ds_read_b128 v[182:185], v153 offset:54272
	ds_read_b128 v[190:193], v153 offset:55296
	ds_read_b128 v[194:197], v153 offset:56320
	global_load_lds_dwordx4 v[150:151], off
	v_lshl_add_u64 v[150:151], v[216:217], 0, s[40:41]
	s_mov_b32 m0, s61
	s_nop 0
	global_load_lds_dwordx4 v[150:151], off
	s_barrier
	s_waitcnt lgkmcnt(0)
	s_setprio 1
	s_waitcnt lgkmcnt(0)
	v_mfma_f32_16x16x32_bf16 v[62:65], v[142:145], v[162:165], v[62:65]
	v_mfma_f32_16x16x32_bf16 v[58:61], v[154:157], v[162:165], v[58:61]
	v_mfma_f32_16x16x32_bf16 v[46:49], v[142:145], v[170:173], v[46:49]
	v_mfma_f32_16x16x32_bf16 v[42:45], v[154:157], v[170:173], v[42:45]
	v_mfma_f32_16x16x32_bf16 v[30:33], v[142:145], v[178:181], v[30:33]
	v_mfma_f32_16x16x32_bf16 v[26:29], v[154:157], v[178:181], v[26:29]
	v_mfma_f32_16x16x32_bf16 v[14:17], v[142:145], v[190:193], v[14:17]
	v_mfma_f32_16x16x32_bf16 v[10:13], v[154:157], v[190:193], v[10:13]
	v_mfma_f32_16x16x32_bf16 v[62:65], v[146:149], v[166:169], v[62:65]
	v_mfma_f32_16x16x32_bf16 v[58:61], v[158:161], v[166:169], v[58:61]
	v_mfma_f32_16x16x32_bf16 v[46:49], v[146:149], v[174:177], v[46:49]
	v_mfma_f32_16x16x32_bf16 v[42:45], v[158:161], v[174:177], v[42:45]
	v_mfma_f32_16x16x32_bf16 v[30:33], v[146:149], v[182:185], v[30:33]
	v_mfma_f32_16x16x32_bf16 v[26:29], v[158:161], v[182:185], v[26:29]
	v_mfma_f32_16x16x32_bf16 v[14:17], v[146:149], v[194:197], v[14:17]
	v_mfma_f32_16x16x32_bf16 v[10:13], v[158:161], v[194:197], v[10:13]
	s_setprio 0
	s_barrier
	s_add_u32 s78, s86, 0x40080
	s_addc_u32 s79, s87, 0
	s_add_i32 s45, s47, s36
	v_lshl_add_u64 v[142:143], s[78:79], 0, v[132:133]
	s_mov_b32 m0, s45
	s_nop 0
	global_load_lds_dwordx4 v[142:143], off
	v_lshl_add_u64 v[142:143], s[78:79], 0, v[136:137]
	s_add_i32 m0, s45, 0x2000
	s_nop 0
	global_load_lds_dwordx4 v[142:143], off
	s_waitcnt vmcnt(10)
	s_barrier
	s_setprio 1
	v_mfma_f32_16x16x32_bf16 v[54:57], v[198:201], v[162:165], v[54:57]
	v_mfma_f32_16x16x32_bf16 v[50:53], v[206:209], v[162:165], v[50:53]
	v_mfma_f32_16x16x32_bf16 v[38:41], v[198:201], v[170:173], v[38:41]
	v_mfma_f32_16x16x32_bf16 v[34:37], v[206:209], v[170:173], v[34:37]
	v_mfma_f32_16x16x32_bf16 v[22:25], v[198:201], v[178:181], v[22:25]
	v_mfma_f32_16x16x32_bf16 v[18:21], v[206:209], v[178:181], v[18:21]
	v_mfma_f32_16x16x32_bf16 v[6:9], v[198:201], v[190:193], v[6:9]
	v_mfma_f32_16x16x32_bf16 v[2:5], v[206:209], v[190:193], v[2:5]
	v_mfma_f32_16x16x32_bf16 v[54:57], v[202:205], v[166:169], v[54:57]
	v_mfma_f32_16x16x32_bf16 v[50:53], v[210:213], v[166:169], v[50:53]
	v_mfma_f32_16x16x32_bf16 v[38:41], v[202:205], v[174:177], v[38:41]
	v_mfma_f32_16x16x32_bf16 v[34:37], v[210:213], v[174:177], v[34:37]
	v_mfma_f32_16x16x32_bf16 v[22:25], v[202:205], v[182:185], v[22:25]
	v_mfma_f32_16x16x32_bf16 v[18:21], v[210:213], v[182:185], v[18:21]
	v_mfma_f32_16x16x32_bf16 v[6:9], v[202:205], v[194:197], v[6:9]
	v_mfma_f32_16x16x32_bf16 v[2:5], v[210:213], v[194:197], v[2:5]
	s_setprio 0
	s_add_i32 s44, s44, 2
	s_add_u32 s6, s6, 0x100
	s_addc_u32 s7, s7, 0
	s_add_u32 s23, s23, 0x100
	s_addc_u32 s34, s34, 0
	s_cmp_gt_u32 s44, 13
	s_barrier
	s_cbranch_scc0 .LBB0_150
	v_mov_b32_e32 v158, v252
	s_lshl_b32 s11, s4, 8
	v_and_b32_e32 v156, 63, v158
	v_or_b32_e32 v0, s72, v156
	v_lshrrev_b32_e32 v0, 1, v0
	v_and_or_b32 v142, v0, 63, s73
	v_add_u32_e32 v144, s11, v142
	v_ashrrev_i32_e32 v145, 31, v144
	v_and_b32_e32 v154, 1, v158
	v_lshlrev_b64 v[144:145], 6, v[144:145]
	v_lshl_add_u64 v[144:145], s[82:83], 0, v[144:145]
	v_lshlrev_b32_e32 v0, 5, v154
	v_lshl_add_u64 v[148:149], v[144:145], 0, v[0:1]
	global_load_dwordx4 v[144:147], v[148:149], off
	s_nop 0
	global_load_dwordx4 v[148:151], v[148:149], off offset:16
	v_lshlrev_b32_e32 v157, 2, v156
	v_cmp_eq_u32_e32 vcc, 0, v154
	s_waitcnt vmcnt(0)
	v_add_f32_e32 v0, v144, v145
	v_add_f32_e32 v143, v146, v147
	v_add_f32_e32 v144, v148, v149
	v_add_f32_e32 v145, v150, v151
	v_add_f32_e32 v0, v0, v143
	v_add_f32_e32 v143, v144, v145
	v_add_f32_e32 v0, v0, v143
	v_xor_b32_e32 v143, 4, v157
	ds_bpermute_b32 v143, v143, v0
	s_and_saveexec_b64 s[4:5], vcc
	s_cbranch_execz .LBB0_153
	s_waitcnt lgkmcnt(0)
	v_add_f32_e32 v0, v0, v143
	v_fmamk_f32 v0, v0, 0x3a800000, v224
	s_mov_b32 s6, 0x800000
	v_mul_f32_e32 v143, 0x4b800000, v0
	v_cmp_gt_f32_e32 vcc, s6, v0
	v_lshl_add_u32 v142, v142, 2, 0
	v_add_u32_e32 v142, 0x20000, v142
	v_cndmask_b32_e32 v0, v0, v143, vcc
	v_rsq_f32_e32 v0, v0
	s_nop 0
	v_mul_f32_e32 v143, 0x45800000, v0
	v_cndmask_b32_e32 v0, v0, v143, vcc
	ds_write_b32 v142, v0

.LBB0_838:
	s_add_u32 s4, s88, 0x100
	s_addc_u32 s5, s89, 0
	s_add_i32 s79, 0, 0x10000
	v_add_u32_e32 v142, s79, v212
	ds_read_b128 v[130:133], v142
	ds_read_b128 v[134:137], v142 offset:1024
	ds_read_b128 v[138:141], v142 offset:2048
	ds_read_b128 v[142:145], v142 offset:3072
	s_cmp_eq_u32 s78, 12
	s_cselect_b32 s93, s17, s5
	s_cselect_b32 s92, s16, s4
	s_cselect_b32 s91, s15, s75
	s_cselect_b32 s90, s23, s34
	v_lshl_add_u64 v[178:179], s[88:89], 0, v[196:197]
	s_add_i32 m0, s39, 0xc000
	ds_read_b128 v[146:149], v213
	ds_read_b128 v[150:153], v213 offset:1024
	ds_read_b128 v[154:157], v213 offset:2048
	ds_read_b128 v[158:161], v213 offset:3072
	ds_read_b128 v[162:165], v213 offset:4096
	ds_read_b128 v[166:169], v213 offset:5120
	ds_read_b128 v[170:173], v213 offset:6144
	ds_read_b128 v[174:177], v213 offset:7168
	global_load_lds_dwordx4 v[178:179], off
	v_lshl_add_u64 v[178:179], s[88:89], 0, v[198:199]
	s_add_i32 m0, s39, 0xe000
	s_nop 0
	global_load_lds_dwordx4 v[178:179], off
	s_waitcnt lgkmcnt(8)
	s_waitcnt vmcnt(10)
	s_barrier
	s_waitcnt lgkmcnt(0)
	s_setprio 1
	s_waitcnt lgkmcnt(0)
	v_mfma_f32_16x16x32_bf16 v[126:129], v[130:133], v[146:149], v[126:129]
	v_mfma_f32_16x16x32_bf16 v[122:125], v[138:141], v[146:149], v[122:125]
	v_mfma_f32_16x16x32_bf16 v[110:113], v[130:133], v[154:157], v[110:113]
	v_mfma_f32_16x16x32_bf16 v[106:109], v[138:141], v[154:157], v[106:109]
	v_mfma_f32_16x16x32_bf16 v[94:97], v[130:133], v[162:165], v[94:97]
	v_mfma_f32_16x16x32_bf16 v[90:93], v[138:141], v[162:165], v[90:93]
	v_mfma_f32_16x16x32_bf16 v[78:81], v[130:133], v[170:173], v[78:81]
	v_mfma_f32_16x16x32_bf16 v[74:77], v[138:141], v[170:173], v[74:77]
	v_mfma_f32_16x16x32_bf16 v[126:129], v[134:137], v[150:153], v[126:129]
	v_mfma_f32_16x16x32_bf16 v[122:125], v[142:145], v[150:153], v[122:125]
	v_mfma_f32_16x16x32_bf16 v[110:113], v[134:137], v[158:161], v[110:113]
	v_mfma_f32_16x16x32_bf16 v[106:109], v[142:145], v[158:161], v[106:109]
	v_mfma_f32_16x16x32_bf16 v[94:97], v[134:137], v[166:169], v[94:97]
	v_mfma_f32_16x16x32_bf16 v[90:93], v[142:145], v[166:169], v[90:93]
	v_mfma_f32_16x16x32_bf16 v[78:81], v[134:137], v[174:177], v[78:81]
	v_mfma_f32_16x16x32_bf16 v[74:77], v[142:145], v[174:177], v[74:77]
	s_setprio 0
	s_barrier
	s_add_i32 s87, 0, 0x14000
	v_add_u32_e32 v186, s87, v212
	s_add_i32 s79, s79, s38
	ds_read_b128 v[178:181], v186
	ds_read_b128 v[182:185], v186 offset:1024
	ds_read_b128 v[200:203], v186 offset:2048
	ds_read_b128 v[204:207], v186 offset:3072
	v_lshl_add_u64 v[186:187], s[90:91], 0, v[0:1]
	s_mov_b32 m0, s79
	v_lshl_add_u64 v[208:209], s[90:91], 0, v[194:195]
	global_load_lds_dwordx4 v[186:187], off
	s_add_i32 m0, s79, 0x2000
	s_nop 0
	global_load_lds_dwordx4 v[208:209], off
	s_waitcnt vmcnt(10)
	s_barrier
	s_waitcnt lgkmcnt(0)
	s_setprio 1
	s_waitcnt lgkmcnt(0)
	v_mfma_f32_16x16x32_bf16 v[118:121], v[178:181], v[146:149], v[118:121]
	v_mfma_f32_16x16x32_bf16 v[114:117], v[200:203], v[146:149], v[114:117]
	v_mfma_f32_16x16x32_bf16 v[102:105], v[178:181], v[154:157], v[102:105]
	v_mfma_f32_16x16x32_bf16 v[98:101], v[200:203], v[154:157], v[98:101]
	v_mfma_f32_16x16x32_bf16 v[86:89], v[178:181], v[162:165], v[86:89]
	v_mfma_f32_16x16x32_bf16 v[82:85], v[200:203], v[162:165], v[82:85]
	v_mfma_f32_16x16x32_bf16 v[70:73], v[178:181], v[170:173], v[70:73]
	v_mfma_f32_16x16x32_bf16 v[66:69], v[200:203], v[170:173], v[66:69]
	v_mfma_f32_16x16x32_bf16 v[118:121], v[182:185], v[150:153], v[118:121]
	v_mfma_f32_16x16x32_bf16 v[114:117], v[204:207], v[150:153], v[114:117]
	v_mfma_f32_16x16x32_bf16 v[102:105], v[182:185], v[158:161], v[102:105]
	v_mfma_f32_16x16x32_bf16 v[98:101], v[204:207], v[158:161], v[98:101]
	v_mfma_f32_16x16x32_bf16 v[86:89], v[182:185], v[166:169], v[86:89]
	v_mfma_f32_16x16x32_bf16 v[82:85], v[204:207], v[166:169], v[82:85]
	v_mfma_f32_16x16x32_bf16 v[70:73], v[182:185], v[174:177], v[70:73]
	v_mfma_f32_16x16x32_bf16 v[66:69], v[204:207], v[174:177], v[66:69]
	s_setprio 0
	s_mov_b32 m0, s39
	v_lshl_add_u64 v[210:211], s[92:93], 0, v[190:191]
	s_barrier
	ds_read_b128 v[146:149], v213 offset:16384
	ds_read_b128 v[150:153], v213 offset:17408
	ds_read_b128 v[154:157], v213 offset:18432
	ds_read_b128 v[158:161], v213 offset:19456
	ds_read_b128 v[162:165], v213 offset:20480
	ds_read_b128 v[166:169], v213 offset:21504
	ds_read_b128 v[170:173], v213 offset:22528
	ds_read_b128 v[174:177], v213 offset:23552
	global_load_lds_dwordx4 v[210:211], off
	v_lshl_add_u64 v[214:215], s[92:93], 0, v[192:193]
	s_mov_b32 m0, s42
	s_nop 0
	global_load_lds_dwordx4 v[214:215], off
	s_barrier
	s_waitcnt lgkmcnt(0)
	s_setprio 1
	s_waitcnt lgkmcnt(0)
	v_mfma_f32_16x16x32_bf16 v[62:65], v[130:133], v[146:149], v[62:65]
	v_mfma_f32_16x16x32_bf16 v[58:61], v[138:141], v[146:149], v[58:61]
	v_mfma_f32_16x16x32_bf16 v[46:49], v[130:133], v[154:157], v[46:49]
	v_mfma_f32_16x16x32_bf16 v[42:45], v[138:141], v[154:157], v[42:45]
	v_mfma_f32_16x16x32_bf16 v[30:33], v[130:133], v[162:165], v[30:33]
	v_mfma_f32_16x16x32_bf16 v[26:29], v[138:141], v[162:165], v[26:29]
	v_mfma_f32_16x16x32_bf16 v[14:17], v[130:133], v[170:173], v[14:17]
	v_mfma_f32_16x16x32_bf16 v[10:13], v[138:141], v[170:173], v[10:13]
	v_mfma_f32_16x16x32_bf16 v[62:65], v[134:137], v[150:153], v[62:65]
	v_mfma_f32_16x16x32_bf16 v[58:61], v[142:145], v[150:153], v[58:61]
	v_mfma_f32_16x16x32_bf16 v[46:49], v[134:137], v[158:161], v[46:49]
	v_mfma_f32_16x16x32_bf16 v[42:45], v[142:145], v[158:161], v[42:45]
	v_mfma_f32_16x16x32_bf16 v[30:33], v[134:137], v[166:169], v[30:33]
	v_mfma_f32_16x16x32_bf16 v[26:29], v[142:145], v[166:169], v[26:29]
	v_mfma_f32_16x16x32_bf16 v[14:17], v[134:137], v[174:177], v[14:17]
	v_mfma_f32_16x16x32_bf16 v[10:13], v[142:145], v[174:177], v[10:13]
	s_setprio 0
	s_barrier
	s_add_u32 s88, s90, 0x40000
	s_addc_u32 s89, s91, 0
	s_add_i32 s79, s87, s38
	v_lshl_add_u64 v[130:131], s[88:89], 0, v[0:1]
	s_mov_b32 m0, s79
	s_nop 0
	global_load_lds_dwordx4 v[130:131], off
	v_lshl_add_u64 v[130:131], s[88:89], 0, v[194:195]
	s_add_i32 m0, s79, 0x2000
	s_nop 0
	global_load_lds_dwordx4 v[130:131], off
	s_waitcnt vmcnt(10)
	s_barrier
	s_setprio 1
	v_mfma_f32_16x16x32_bf16 v[54:57], v[178:181], v[146:149], v[54:57]
	v_mfma_f32_16x16x32_bf16 v[50:53], v[200:203], v[146:149], v[50:53]
	v_mfma_f32_16x16x32_bf16 v[38:41], v[178:181], v[154:157], v[38:41]
	v_mfma_f32_16x16x32_bf16 v[34:37], v[200:203], v[154:157], v[34:37]
	v_mfma_f32_16x16x32_bf16 v[22:25], v[178:181], v[162:165], v[22:25]
	v_mfma_f32_16x16x32_bf16 v[18:21], v[200:203], v[162:165], v[18:21]
	v_mfma_f32_16x16x32_bf16 v[6:9], v[178:181], v[170:173], v[6:9]
	v_mfma_f32_16x16x32_bf16 v[2:5], v[200:203], v[170:173], v[2:5]
	v_mfma_f32_16x16x32_bf16 v[54:57], v[182:185], v[150:153], v[54:57]
	v_mfma_f32_16x16x32_bf16 v[50:53], v[204:207], v[150:153], v[50:53]
	v_mfma_f32_16x16x32_bf16 v[38:41], v[182:185], v[158:161], v[38:41]
	v_mfma_f32_16x16x32_bf16 v[34:37], v[204:207], v[158:161], v[34:37]
	v_mfma_f32_16x16x32_bf16 v[22:25], v[182:185], v[166:169], v[22:25]
	v_mfma_f32_16x16x32_bf16 v[18:21], v[204:207], v[166:169], v[18:21]
	v_mfma_f32_16x16x32_bf16 v[6:9], v[182:185], v[174:177], v[6:9]
	v_mfma_f32_16x16x32_bf16 v[2:5], v[204:207], v[174:177], v[2:5]
	s_setprio 0
	s_add_i32 s79, 0, 0x18000
	v_add_u32_e32 v142, s79, v212
	s_barrier
	ds_read_b128 v[130:133], v142
	ds_read_b128 v[134:137], v142 offset:1024
	ds_read_b128 v[138:141], v142 offset:2048
	ds_read_b128 v[142:145], v142 offset:3072
	s_add_u32 s88, s92, 0xc0000
	s_addc_u32 s89, s93, 0
	s_mov_b32 m0, s43
	v_lshl_add_u64 v[178:179], s[88:89], 0, v[190:191]
	ds_read_b128 v[146:149], v213 offset:32768
	ds_read_b128 v[150:153], v213 offset:33792
	ds_read_b128 v[154:157], v213 offset:34816
	ds_read_b128 v[158:161], v213 offset:35840
	ds_read_b128 v[162:165], v213 offset:36864
	ds_read_b128 v[166:169], v213 offset:37888
	ds_read_b128 v[170:173], v213 offset:38912
	ds_read_b128 v[174:177], v213 offset:39936
	global_load_lds_dwordx4 v[178:179], off
	v_lshl_add_u64 v[178:179], s[88:89], 0, v[192:193]
	s_mov_b32 m0, s44
	s_nop 0
	global_load_lds_dwordx4 v[178:179], off
	s_waitcnt lgkmcnt(8)
	s_waitcnt vmcnt(10)
	s_barrier
	s_waitcnt lgkmcnt(0)
	s_setprio 1
	s_waitcnt lgkmcnt(0)
	v_mfma_f32_16x16x32_bf16 v[126:129], v[130:133], v[146:149], v[126:129]
	v_mfma_f32_16x16x32_bf16 v[122:125], v[138:141], v[146:149], v[122:125]
	v_mfma_f32_16x16x32_bf16 v[110:113], v[130:133], v[154:157], v[110:113]
	v_mfma_f32_16x16x32_bf16 v[106:109], v[138:141], v[154:157], v[106:109]
	v_mfma_f32_16x16x32_bf16 v[94:97], v[130:133], v[162:165], v[94:97]
	v_mfma_f32_16x16x32_bf16 v[90:93], v[138:141], v[162:165], v[90:93]
	v_mfma_f32_16x16x32_bf16 v[78:81], v[130:133], v[170:173], v[78:81]
	v_mfma_f32_16x16x32_bf16 v[74:77], v[138:141], v[170:173], v[74:77]
	v_mfma_f32_16x16x32_bf16 v[126:129], v[134:137], v[150:153], v[126:129]
	v_mfma_f32_16x16x32_bf16 v[122:125], v[142:145], v[150:153], v[122:125]
	v_mfma_f32_16x16x32_bf16 v[110:113], v[134:137], v[158:161], v[110:113]
	v_mfma_f32_16x16x32_bf16 v[106:109], v[142:145], v[158:161], v[106:109]
	v_mfma_f32_16x16x32_bf16 v[94:97], v[134:137], v[166:169], v[94:97]
	v_mfma_f32_16x16x32_bf16 v[90:93], v[142:145], v[166:169], v[90:93]
	v_mfma_f32_16x16x32_bf16 v[78:81], v[134:137], v[174:177], v[78:81]
	v_mfma_f32_16x16x32_bf16 v[74:77], v[142:145], v[174:177], v[74:77]
	s_setprio 0
	s_barrier
	s_add_i32 s87, 0, 0x1c000
	s_add_i32 s79, s79, s38
	v_add_u32_e32 v204, s87, v212
	v_lshl_add_u64 v[186:187], v[186:187], 0, s[40:41]
	s_mov_b32 m0, s79
	ds_read_b128 v[178:181], v204
	ds_read_b128 v[182:185], v204 offset:1024
	ds_read_b128 v[200:203], v204 offset:2048
	ds_read_b128 v[204:207], v204 offset:3072
	global_load_lds_dwordx4 v[186:187], off
	v_lshl_add_u64 v[186:187], v[208:209], 0, s[40:41]
	s_add_i32 m0, s79, 0x2000
	s_nop 0
	global_load_lds_dwordx4 v[186:187], off
	s_waitcnt vmcnt(10)
	s_barrier
	s_waitcnt lgkmcnt(0)
	s_setprio 1
	s_waitcnt lgkmcnt(0)
	v_mfma_f32_16x16x32_bf16 v[118:121], v[178:181], v[146:149], v[118:121]
	v_mfma_f32_16x16x32_bf16 v[114:117], v[200:203], v[146:149], v[114:117]
	v_mfma_f32_16x16x32_bf16 v[102:105], v[178:181], v[154:157], v[102:105]
	v_mfma_f32_16x16x32_bf16 v[98:101], v[200:203], v[154:157], v[98:101]
	v_mfma_f32_16x16x32_bf16 v[86:89], v[178:181], v[162:165], v[86:89]
	v_mfma_f32_16x16x32_bf16 v[82:85], v[200:203], v[162:165], v[82:85]
	v_mfma_f32_16x16x32_bf16 v[70:73], v[178:181], v[170:173], v[70:73]
	v_mfma_f32_16x16x32_bf16 v[66:69], v[200:203], v[170:173], v[66:69]
	v_mfma_f32_16x16x32_bf16 v[118:121], v[182:185], v[150:153], v[118:121]
	v_mfma_f32_16x16x32_bf16 v[114:117], v[204:207], v[150:153], v[114:117]
	v_mfma_f32_16x16x32_bf16 v[102:105], v[182:185], v[158:161], v[102:105]
	v_mfma_f32_16x16x32_bf16 v[98:101], v[204:207], v[158:161], v[98:101]
	v_mfma_f32_16x16x32_bf16 v[86:89], v[182:185], v[166:169], v[86:89]
	v_mfma_f32_16x16x32_bf16 v[82:85], v[204:207], v[166:169], v[82:85]
	v_mfma_f32_16x16x32_bf16 v[70:73], v[182:185], v[174:177], v[70:73]
	v_mfma_f32_16x16x32_bf16 v[66:69], v[204:207], v[174:177], v[66:69]
	s_setprio 0
	s_mov_b32 m0, s60
	v_lshl_add_u64 v[186:187], v[210:211], 0, s[40:41]
	s_barrier
	ds_read_b128 v[146:149], v213 offset:49152
	ds_read_b128 v[150:153], v213 offset:50176
	ds_read_b128 v[154:157], v213 offset:51200
	ds_read_b128 v[158:161], v213 offset:52224
	ds_read_b128 v[162:165], v213 offset:53248
	ds_read_b128 v[166:169], v213 offset:54272
	ds_read_b128 v[170:173], v213 offset:55296
	ds_read_b128 v[174:177], v213 offset:56320
	global_load_lds_dwordx4 v[186:187], off
	v_lshl_add_u64 v[186:187], v[214:215], 0, s[40:41]
	s_mov_b32 m0, s61
	s_nop 0
	global_load_lds_dwordx4 v[186:187], off
	s_barrier
	s_waitcnt lgkmcnt(0)
	s_setprio 1
	s_waitcnt lgkmcnt(0)
	v_mfma_f32_16x16x32_bf16 v[62:65], v[130:133], v[146:149], v[62:65]
	v_mfma_f32_16x16x32_bf16 v[58:61], v[138:141], v[146:149], v[58:61]
	v_mfma_f32_16x16x32_bf16 v[46:49], v[130:133], v[154:157], v[46:49]
	v_mfma_f32_16x16x32_bf16 v[42:45], v[138:141], v[154:157], v[42:45]
	v_mfma_f32_16x16x32_bf16 v[30:33], v[130:133], v[162:165], v[30:33]
	v_mfma_f32_16x16x32_bf16 v[26:29], v[138:141], v[162:165], v[26:29]
	v_mfma_f32_16x16x32_bf16 v[14:17], v[130:133], v[170:173], v[14:17]
	v_mfma_f32_16x16x32_bf16 v[10:13], v[138:141], v[170:173], v[10:13]
	v_mfma_f32_16x16x32_bf16 v[62:65], v[134:137], v[150:153], v[62:65]
	v_mfma_f32_16x16x32_bf16 v[58:61], v[142:145], v[150:153], v[58:61]
	v_mfma_f32_16x16x32_bf16 v[46:49], v[134:137], v[158:161], v[46:49]
	v_mfma_f32_16x16x32_bf16 v[42:45], v[142:145], v[158:161], v[42:45]
	v_mfma_f32_16x16x32_bf16 v[30:33], v[134:137], v[166:169], v[30:33]
	v_mfma_f32_16x16x32_bf16 v[26:29], v[142:145], v[166:169], v[26:29]
	v_mfma_f32_16x16x32_bf16 v[14:17], v[134:137], v[174:177], v[14:17]
	v_mfma_f32_16x16x32_bf16 v[10:13], v[142:145], v[174:177], v[10:13]
	s_setprio 0
	s_barrier
	s_add_u32 s88, s90, 0x40080
	s_addc_u32 s89, s91, 0
	s_add_i32 s79, s87, s38
	v_lshl_add_u64 v[130:131], s[88:89], 0, v[0:1]
	s_mov_b32 m0, s79
	s_nop 0
	global_load_lds_dwordx4 v[130:131], off
	v_lshl_add_u64 v[130:131], s[88:89], 0, v[194:195]
	s_add_i32 m0, s79, 0x2000
	s_nop 0
	global_load_lds_dwordx4 v[130:131], off
	s_waitcnt vmcnt(10)
	s_barrier
	s_setprio 1
	v_mfma_f32_16x16x32_bf16 v[54:57], v[178:181], v[146:149], v[54:57]
	v_mfma_f32_16x16x32_bf16 v[50:53], v[200:203], v[146:149], v[50:53]
	v_mfma_f32_16x16x32_bf16 v[38:41], v[178:181], v[154:157], v[38:41]
	v_mfma_f32_16x16x32_bf16 v[34:37], v[200:203], v[154:157], v[34:37]
	v_mfma_f32_16x16x32_bf16 v[22:25], v[178:181], v[162:165], v[22:25]
	v_mfma_f32_16x16x32_bf16 v[18:21], v[200:203], v[162:165], v[18:21]
	v_mfma_f32_16x16x32_bf16 v[6:9], v[178:181], v[170:173], v[6:9]
	v_mfma_f32_16x16x32_bf16 v[2:5], v[200:203], v[170:173], v[2:5]
	v_mfma_f32_16x16x32_bf16 v[54:57], v[182:185], v[150:153], v[54:57]
	v_mfma_f32_16x16x32_bf16 v[50:53], v[204:207], v[150:153], v[50:53]
	v_mfma_f32_16x16x32_bf16 v[38:41], v[182:185], v[158:161], v[38:41]
	v_mfma_f32_16x16x32_bf16 v[34:37], v[204:207], v[158:161], v[34:37]
	v_mfma_f32_16x16x32_bf16 v[22:25], v[182:185], v[166:169], v[22:25]
	v_mfma_f32_16x16x32_bf16 v[18:21], v[204:207], v[166:169], v[18:21]
	v_mfma_f32_16x16x32_bf16 v[6:9], v[182:185], v[174:177], v[6:9]
	v_mfma_f32_16x16x32_bf16 v[2:5], v[204:207], v[174:177], v[2:5]
	s_setprio 0
	s_add_i32 s78, s78, 2
	s_add_u32 s34, s34, 0x100
	s_addc_u32 s75, s75, 0
	s_cmp_gt_u32 s78, 13
	s_mov_b64 s[88:89], s[4:5]
	s_barrier
	s_cbranch_scc0 .LBB0_838
	s_lshl_b32 s4, s22, 8
	v_mov_b32_e32 v186, v252
	s_add_i32 s4, s4, s47
	s_nop 0
	v_and_or_b32 v202, v186, 15, s4
	s_lshl_b32 s4, s86, 8
	s_or_b32 s4, s4, s55
	v_lshrrev_b32_e32 v130, 1, v186
	v_and_or_b32 v200, v130, 24, s4
	v_ashrrev_i32_e32 v201, 31, v200
	v_ashrrev_i32_e32 v203, 31, v202
	v_lshl_add_u64 v[204:205], v[200:201], 2, s[6:7]
	v_lshlrev_b64 v[130:131], 12, v[202:203]
	v_lshl_add_u64 v[130:131], v[204:205], 0, v[130:131]
	global_load_dwordx4 v[216:219], v[130:131], off offset:16
	global_load_dwordx4 v[220:223], v[130:131], off
	global_load_dwordx4 v[178:181], v[130:131], off offset:528
	global_load_dwordx4 v[182:185], v[130:131], off offset:512
	v_or_b32_e32 v210, 16, v202
	v_ashrrev_i32_e32 v211, 31, v210
	v_lshlrev_b64 v[130:131], 12, v[210:211]
	v_or_b32_e32 v208, 32, v202
	v_lshl_add_u64 v[130:131], v[204:205], 0, v[130:131]
	v_ashrrev_i32_e32 v209, 31, v208
	global_load_dwordx4 v[170:173], v[130:131], off offset:16
	global_load_dwordx4 v[174:177], v[130:131], off
	global_load_dwordx4 v[162:165], v[130:131], off offset:528
	global_load_dwordx4 v[166:169], v[130:131], off offset:512
	v_lshlrev_b64 v[130:131], 12, v[208:209]
	v_or_b32_e32 v206, 48, v202
	v_lshl_add_u64 v[130:131], v[204:205], 0, v[130:131]
	v_ashrrev_i32_e32 v207, 31, v206
	global_load_dwordx4 v[154:157], v[130:131], off offset:16
	global_load_dwordx4 v[158:161], v[130:131], off
	global_load_dwordx4 v[138:141], v[130:131], off offset:528
	global_load_dwordx4 v[142:145], v[130:131], off offset:512
	v_lshlrev_b64 v[130:131], 12, v[206:207]
	v_lshl_add_u64 v[134:135], v[204:205], 0, v[130:131]
	global_load_dwordx4 v[146:149], v[134:135], off offset:16
	global_load_dwordx4 v[150:153], v[134:135], off
	global_load_dwordx4 v[130:133], v[134:135], off offset:528
	s_nop 0
	global_load_dwordx4 v[134:137], v[134:135], off offset:512
	v_and_b32_e32 v186, 63, v186
	v_lshlrev_b32_e32 v187, 2, v186
	v_xor_b32_e32 v215, 64, v187
	v_xor_b32_e32 v214, 0x80, v187
	v_cmp_gt_u32_e32 vcc, 16, v186
	v_lshlrev_b64 v[186:187], 10, v[202:203]
	v_lshl_add_u64 v[186:187], v[186:187], 0, v[200:201]
	s_lshl_b32 s4, s86, 2
	s_ashr_i32 s5, s4, 31
	s_waitcnt vmcnt(0)
	v_pk_add_f32 v[124:125], v[124:125], v[218:219]
	v_pk_add_f32 v[128:129], v[128:129], v[222:223]
	v_pk_add_f32 v[126:127], v[126:127], v[220:221]
	v_pk_mul_f32 v[218:219], v[128:129], v[128:129]
	v_pk_mul_f32 v[220:221], v[126:127], v[126:127]
	v_pk_add_f32 v[122:123], v[122:123], v[216:217]
	v_lshl_add_u64 v[216:217], v[186:187], 2, s[12:13]
	v_add_f32_e32 v220, v220, v221
	v_add_f32_e32 v218, v218, v219
	global_store_dwordx4 v[216:217], v[126:129], off
	global_store_dwordx4 v[216:217], v[122:125], off offset:16
	v_add_f32_e32 v222, v220, v218
	v_pk_mul_f32 v[220:221], v[122:123], v[122:123]
	v_cvt_pk_bf16_f32 v126, v126, v127
	v_cvt_pk_bf16_f32 v127, v128, v129
	v_cvt_pk_bf16_f32 v128, v122, v123
	v_cvt_pk_bf16_f32 v129, v124, v125
	v_lshl_add_u64 v[122:123], v[186:187], 1, s[8:9]
	v_pk_add_f32 v[120:121], v[120:121], v[184:185]
	v_pk_add_f32 v[118:119], v[118:119], v[182:183]
	v_pk_mul_f32 v[218:219], v[124:125], v[124:125]
	global_store_dwordx4 v[122:123], v[126:129], off
	v_pk_mul_f32 v[124:125], v[120:121], v[120:121]
	v_pk_add_f32 v[116:117], v[116:117], v[180:181]
	v_pk_mul_f32 v[126:127], v[118:119], v[118:119]
	v_pk_add_f32 v[114:115], v[114:115], v[178:179]
	v_add_f32_e32 v126, v126, v127
	v_add_f32_e32 v124, v124, v125
	v_add_f32_e32 v128, v126, v124
	v_pk_mul_f32 v[124:125], v[116:117], v[116:117]
	v_pk_mul_f32 v[126:127], v[114:115], v[114:115]
	v_add_f32_e32 v220, v220, v221
	v_add_f32_e32 v218, v218, v219
	v_add_f32_e32 v126, v126, v127
	v_add_f32_e32 v124, v124, v125
	v_add_f32_e32 v218, v220, v218
	v_add_f32_e32 v124, v126, v124
	v_add_f32_e32 v218, v222, v218
	v_add_f32_e32 v124, v128, v124
	v_add_f32_e32 v124, v218, v124
	global_store_dwordx4 v[216:217], v[118:121], off offset:512
	global_store_dwordx4 v[216:217], v[114:117], off offset:528
	s_nop 0
	v_cvt_pk_bf16_f32 v118, v118, v119
	v_cvt_pk_bf16_f32 v119, v120, v121
	v_cvt_pk_bf16_f32 v120, v114, v115
	ds_bpermute_b32 v114, v215, v124
	v_cvt_pk_bf16_f32 v121, v116, v117
	global_store_dwordx4 v[122:123], v[118:121], off offset:256
	s_waitcnt lgkmcnt(0)
	v_add_f32_e32 v114, v124, v114
	ds_bpermute_b32 v115, v214, v114
	s_and_saveexec_b64 s[22:23], vcc
	s_cbranch_execz .LBB0_841
	v_lshlrev_b64 v[116:117], 6, v[202:203]
	v_lshl_add_u64 v[116:117], s[10:11], 0, v[116:117]
	v_lshl_add_u64 v[116:117], s[4:5], 2, v[116:117]
	s_lshl_b32 s34, s45, 2
	v_lshl_add_u64 v[116:117], v[116:117], 0, s[34:35]
	s_waitcnt lgkmcnt(0)
	v_add_f32_e32 v114, v114, v115
	global_store_dword v[116:117], v114, off

.LBB0_919:
	s_add_u32 s88, s6, 0x100
	s_addc_u32 s89, s7, 0
	s_add_i32 vcc_lo, 0, 0x10000
	v_add_u32_e32 v0, vcc_lo, v254
	ds_read_b128 v[130:133], v0
	ds_read_b128 v[134:137], v0 offset:1024
	ds_read_b128 v[138:141], v0 offset:2048
	ds_read_b128 v[142:145], v0 offset:3072
	s_cmp_eq_u32 s45, 12
	s_cselect_b32 s93, s17, s89
	s_cselect_b32 s92, s22, s88
	s_cselect_b32 s91, s15, s29
	s_cselect_b32 s90, s23, s28
	v_lshl_add_u64 v[154:155], s[6:7], 0, v[164:165]
	s_add_i32 m0, s43, 0xc000
	ds_read_b128 v[146:149], v253
	ds_read_b128 v[150:153], v253 offset:1024
	ds_read_b128 v[168:171], v253 offset:2048
	ds_read_b128 v[172:175], v253 offset:3072
	ds_read_b128 v[176:179], v253 offset:4096
	ds_read_b128 v[180:183], v253 offset:5120
	ds_read_b128 v[184:187], v253 offset:6144
	ds_read_b128 v[190:193], v253 offset:7168
	global_load_lds_dwordx4 v[154:155], off
	v_lshl_add_u64 v[154:155], s[6:7], 0, v[166:167]
	s_add_i32 m0, s43, 0xe000
	s_nop 0
	global_load_lds_dwordx4 v[154:155], off
	s_waitcnt lgkmcnt(8)
	s_waitcnt vmcnt(10)
	s_barrier
	s_waitcnt lgkmcnt(0)
	s_setprio 1
	s_waitcnt lgkmcnt(0)
	v_mfma_f32_16x16x32_bf16 v[126:129], v[130:133], v[146:149], v[126:129]
	v_mfma_f32_16x16x32_bf16 v[70:73], v[138:141], v[146:149], v[70:73]
	v_mfma_f32_16x16x32_bf16 v[122:125], v[130:133], v[168:171], v[122:125]
	v_mfma_f32_16x16x32_bf16 v[74:77], v[138:141], v[168:171], v[74:77]
	v_mfma_f32_16x16x32_bf16 v[114:117], v[130:133], v[176:179], v[114:117]
	v_mfma_f32_16x16x32_bf16 v[66:69], v[138:141], v[176:179], v[66:69]
	v_mfma_f32_16x16x32_bf16 v[110:113], v[130:133], v[184:187], v[110:113]
	v_mfma_f32_16x16x32_bf16 v[78:81], v[138:141], v[184:187], v[78:81]
	v_mfma_f32_16x16x32_bf16 v[126:129], v[134:137], v[150:153], v[126:129]
	v_mfma_f32_16x16x32_bf16 v[70:73], v[142:145], v[150:153], v[70:73]
	v_mfma_f32_16x16x32_bf16 v[122:125], v[134:137], v[172:175], v[122:125]
	v_mfma_f32_16x16x32_bf16 v[74:77], v[142:145], v[172:175], v[74:77]
	v_mfma_f32_16x16x32_bf16 v[114:117], v[134:137], v[180:183], v[114:117]
	v_mfma_f32_16x16x32_bf16 v[66:69], v[142:145], v[180:183], v[66:69]
	v_mfma_f32_16x16x32_bf16 v[110:113], v[134:137], v[190:193], v[110:113]
	v_mfma_f32_16x16x32_bf16 v[78:81], v[142:145], v[190:193], v[78:81]
	s_setprio 0
	s_barrier
	s_add_i32 vcc_hi, 0, 0x14000
	s_add_i32 s6, vcc_lo, s39
	v_add_u32_e32 v0, vcc_hi, v254
	v_lshl_add_u64 v[154:155], s[90:91], 0, v[160:161]
	s_mov_b32 m0, s6
	ds_read_b128 v[194:197], v0
	ds_read_b128 v[198:201], v0 offset:1024
	ds_read_b128 v[202:205], v0 offset:2048
	ds_read_b128 v[206:209], v0 offset:3072
	global_load_lds_dwordx4 v[154:155], off
	v_lshl_add_u64 v[210:211], s[90:91], 0, v[156:157]
	s_add_i32 m0, s6, 0x2000
	s_nop 0
	global_load_lds_dwordx4 v[210:211], off
	s_waitcnt vmcnt(10)
	s_barrier
	s_waitcnt lgkmcnt(0)
	s_setprio 1
	s_waitcnt lgkmcnt(0)
	v_mfma_f32_16x16x32_bf16 v[118:121], v[194:197], v[146:149], v[118:121]
	v_mfma_f32_16x16x32_bf16 v[94:97], v[202:205], v[146:149], v[94:97]
	v_mfma_f32_16x16x32_bf16 v[106:109], v[194:197], v[168:171], v[106:109]
	v_mfma_f32_16x16x32_bf16 v[90:93], v[202:205], v[168:171], v[90:93]
	v_mfma_f32_16x16x32_bf16 v[102:105], v[194:197], v[176:179], v[102:105]
	v_mfma_f32_16x16x32_bf16 v[82:85], v[202:205], v[176:179], v[82:85]
	v_mfma_f32_16x16x32_bf16 v[98:101], v[194:197], v[184:187], v[98:101]
	v_mfma_f32_16x16x32_bf16 v[86:89], v[202:205], v[184:187], v[86:89]
	v_mfma_f32_16x16x32_bf16 v[118:121], v[198:201], v[150:153], v[118:121]
	v_mfma_f32_16x16x32_bf16 v[94:97], v[206:209], v[150:153], v[94:97]
	v_mfma_f32_16x16x32_bf16 v[106:109], v[198:201], v[172:175], v[106:109]
	v_mfma_f32_16x16x32_bf16 v[90:93], v[206:209], v[172:175], v[90:93]
	v_mfma_f32_16x16x32_bf16 v[102:105], v[198:201], v[180:183], v[102:105]
	v_mfma_f32_16x16x32_bf16 v[82:85], v[206:209], v[180:183], v[82:85]
	v_mfma_f32_16x16x32_bf16 v[98:101], v[198:201], v[190:193], v[98:101]
	v_mfma_f32_16x16x32_bf16 v[86:89], v[206:209], v[190:193], v[86:89]
	s_setprio 0
	s_mov_b32 m0, s43
	v_lshl_add_u64 v[212:213], s[92:93], 0, v[162:163]
	s_barrier
	ds_read_b128 v[146:149], v253 offset:16384
	ds_read_b128 v[150:153], v253 offset:17408
	ds_read_b128 v[168:171], v253 offset:18432
	ds_read_b128 v[172:175], v253 offset:19456
	ds_read_b128 v[176:179], v253 offset:20480
	ds_read_b128 v[180:183], v253 offset:21504
	ds_read_b128 v[184:187], v253 offset:22528
	ds_read_b128 v[190:193], v253 offset:23552
	global_load_lds_dwordx4 v[212:213], off
	v_lshl_add_u64 v[214:215], s[92:93], 0, v[158:159]
	s_mov_b32 m0, s60
	s_nop 0
	global_load_lds_dwordx4 v[214:215], off
	s_barrier
	s_waitcnt lgkmcnt(0)
	s_setprio 1
	s_waitcnt lgkmcnt(0)
	v_mfma_f32_16x16x32_bf16 v[62:65], v[130:133], v[146:149], v[62:65]
	v_mfma_f32_16x16x32_bf16 v[10:13], v[138:141], v[146:149], v[10:13]
	v_mfma_f32_16x16x32_bf16 v[58:61], v[130:133], v[168:171], v[58:61]
	v_mfma_f32_16x16x32_bf16 v[14:17], v[138:141], v[168:171], v[14:17]
	v_mfma_f32_16x16x32_bf16 v[54:57], v[130:133], v[176:179], v[54:57]
	v_mfma_f32_16x16x32_bf16 v[6:9], v[138:141], v[176:179], v[6:9]
	v_mfma_f32_16x16x32_bf16 v[42:45], v[130:133], v[184:187], v[42:45]
	v_mfma_f32_16x16x32_bf16 v[2:5], v[138:141], v[184:187], v[2:5]
	v_mfma_f32_16x16x32_bf16 v[62:65], v[134:137], v[150:153], v[62:65]
	v_mfma_f32_16x16x32_bf16 v[10:13], v[142:145], v[150:153], v[10:13]
	v_mfma_f32_16x16x32_bf16 v[58:61], v[134:137], v[172:175], v[58:61]
	v_mfma_f32_16x16x32_bf16 v[14:17], v[142:145], v[172:175], v[14:17]
	v_mfma_f32_16x16x32_bf16 v[54:57], v[134:137], v[180:183], v[54:57]
	v_mfma_f32_16x16x32_bf16 v[6:9], v[142:145], v[180:183], v[6:9]
	v_mfma_f32_16x16x32_bf16 v[42:45], v[134:137], v[190:193], v[42:45]
	v_mfma_f32_16x16x32_bf16 v[2:5], v[142:145], v[190:193], v[2:5]
	s_setprio 0
	s_barrier
	s_add_u32 s6, s90, 0x40000
	s_addc_u32 s7, s91, 0
	s_add_i32 vcc_lo, vcc_hi, s39
	v_lshl_add_u64 v[130:131], s[6:7], 0, v[160:161]
	s_mov_b32 m0, vcc_lo
	s_nop 0
	global_load_lds_dwordx4 v[130:131], off
	v_lshl_add_u64 v[130:131], s[6:7], 0, v[156:157]
	s_add_i32 m0, vcc_lo, 0x2000
	s_nop 0
	global_load_lds_dwordx4 v[130:131], off
	s_waitcnt vmcnt(10)
	s_barrier
	s_setprio 1
	v_mfma_f32_16x16x32_bf16 v[50:53], v[194:197], v[146:149], v[50:53]
	v_mfma_f32_16x16x32_bf16 v[26:29], v[202:205], v[146:149], v[26:29]
	v_mfma_f32_16x16x32_bf16 v[46:49], v[194:197], v[168:171], v[46:49]
	v_mfma_f32_16x16x32_bf16 v[30:33], v[202:205], v[168:171], v[30:33]
	v_mfma_f32_16x16x32_bf16 v[38:41], v[194:197], v[176:179], v[38:41]
	v_mfma_f32_16x16x32_bf16 v[22:25], v[202:205], v[176:179], v[22:25]
	v_mfma_f32_16x16x32_bf16 v[34:37], v[194:197], v[184:187], v[34:37]
	v_mfma_f32_16x16x32_bf16 v[18:21], v[202:205], v[184:187], v[18:21]
	v_mfma_f32_16x16x32_bf16 v[50:53], v[198:201], v[150:153], v[50:53]
	v_mfma_f32_16x16x32_bf16 v[26:29], v[206:209], v[150:153], v[26:29]
	v_mfma_f32_16x16x32_bf16 v[46:49], v[198:201], v[172:175], v[46:49]
	v_mfma_f32_16x16x32_bf16 v[30:33], v[206:209], v[172:175], v[30:33]
	v_mfma_f32_16x16x32_bf16 v[38:41], v[198:201], v[180:183], v[38:41]
	v_mfma_f32_16x16x32_bf16 v[22:25], v[206:209], v[180:183], v[22:25]
	v_mfma_f32_16x16x32_bf16 v[34:37], v[198:201], v[190:193], v[34:37]
	v_mfma_f32_16x16x32_bf16 v[18:21], v[206:209], v[190:193], v[18:21]
	s_setprio 0
	s_add_i32 vcc_lo, 0, 0x18000
	v_add_u32_e32 v0, vcc_lo, v254
	s_barrier
	ds_read_b128 v[130:133], v0
	ds_read_b128 v[134:137], v0 offset:1024
	ds_read_b128 v[138:141], v0 offset:2048
	ds_read_b128 v[142:145], v0 offset:3072
	s_add_u32 s6, s92, 0x40000
	s_addc_u32 s7, s93, 0
	s_mov_b32 m0, s61
	v_lshl_add_u64 v[194:195], s[6:7], 0, v[162:163]
	ds_read_b128 v[146:149], v253 offset:32768
	ds_read_b128 v[150:153], v253 offset:33792
	ds_read_b128 v[168:171], v253 offset:34816
	ds_read_b128 v[172:175], v253 offset:35840
	ds_read_b128 v[176:179], v253 offset:36864
	ds_read_b128 v[180:183], v253 offset:37888
	ds_read_b128 v[184:187], v253 offset:38912
	ds_read_b128 v[190:193], v253 offset:39936
	global_load_lds_dwordx4 v[194:195], off
	v_lshl_add_u64 v[194:195], s[6:7], 0, v[158:159]
	s_mov_b32 m0, s72
	s_nop 0
	global_load_lds_dwordx4 v[194:195], off
	s_waitcnt lgkmcnt(8)
	s_waitcnt vmcnt(10)
	s_barrier
	s_waitcnt lgkmcnt(0)
	s_setprio 1
	s_waitcnt lgkmcnt(0)
	v_mfma_f32_16x16x32_bf16 v[126:129], v[130:133], v[146:149], v[126:129]
	v_mfma_f32_16x16x32_bf16 v[70:73], v[138:141], v[146:149], v[70:73]
	v_mfma_f32_16x16x32_bf16 v[122:125], v[130:133], v[168:171], v[122:125]
	v_mfma_f32_16x16x32_bf16 v[74:77], v[138:141], v[168:171], v[74:77]
	v_mfma_f32_16x16x32_bf16 v[114:117], v[130:133], v[176:179], v[114:117]
	v_mfma_f32_16x16x32_bf16 v[66:69], v[138:141], v[176:179], v[66:69]
	v_mfma_f32_16x16x32_bf16 v[110:113], v[130:133], v[184:187], v[110:113]
	v_mfma_f32_16x16x32_bf16 v[78:81], v[138:141], v[184:187], v[78:81]
	v_mfma_f32_16x16x32_bf16 v[126:129], v[134:137], v[150:153], v[126:129]
	v_mfma_f32_16x16x32_bf16 v[70:73], v[142:145], v[150:153], v[70:73]
	v_mfma_f32_16x16x32_bf16 v[122:125], v[134:137], v[172:175], v[122:125]
	v_mfma_f32_16x16x32_bf16 v[74:77], v[142:145], v[172:175], v[74:77]
	v_mfma_f32_16x16x32_bf16 v[114:117], v[134:137], v[180:183], v[114:117]
	v_mfma_f32_16x16x32_bf16 v[66:69], v[142:145], v[180:183], v[66:69]
	v_mfma_f32_16x16x32_bf16 v[110:113], v[134:137], v[190:193], v[110:113]
	v_mfma_f32_16x16x32_bf16 v[78:81], v[142:145], v[190:193], v[78:81]
	s_setprio 0
	s_barrier
	s_add_i32 s92, 0, 0x1c000
	s_add_i32 s6, vcc_lo, s39
	v_add_u32_e32 v0, s92, v254
	v_lshl_add_u64 v[154:155], v[154:155], 0, s[40:41]
	s_mov_b32 m0, s6
	ds_read_b128 v[194:197], v0
	ds_read_b128 v[198:201], v0 offset:1024
	ds_read_b128 v[202:205], v0 offset:2048
	ds_read_b128 v[206:209], v0 offset:3072
	global_load_lds_dwordx4 v[154:155], off
	v_lshl_add_u64 v[154:155], v[210:211], 0, s[40:41]
	s_add_i32 m0, s6, 0x2000
	s_nop 0
	global_load_lds_dwordx4 v[154:155], off
	s_waitcnt vmcnt(10)
	s_barrier
	s_waitcnt lgkmcnt(0)
	s_setprio 1
	s_waitcnt lgkmcnt(0)
	v_mfma_f32_16x16x32_bf16 v[118:121], v[194:197], v[146:149], v[118:121]
	v_mfma_f32_16x16x32_bf16 v[94:97], v[202:205], v[146:149], v[94:97]
	v_mfma_f32_16x16x32_bf16 v[106:109], v[194:197], v[168:171], v[106:109]
	v_mfma_f32_16x16x32_bf16 v[90:93], v[202:205], v[168:171], v[90:93]
	v_mfma_f32_16x16x32_bf16 v[102:105], v[194:197], v[176:179], v[102:105]
	v_mfma_f32_16x16x32_bf16 v[82:85], v[202:205], v[176:179], v[82:85]
	v_mfma_f32_16x16x32_bf16 v[98:101], v[194:197], v[184:187], v[98:101]
	v_mfma_f32_16x16x32_bf16 v[86:89], v[202:205], v[184:187], v[86:89]
	v_mfma_f32_16x16x32_bf16 v[118:121], v[198:201], v[150:153], v[118:121]
	v_mfma_f32_16x16x32_bf16 v[94:97], v[206:209], v[150:153], v[94:97]
	v_mfma_f32_16x16x32_bf16 v[106:109], v[198:201], v[172:175], v[106:109]
	v_mfma_f32_16x16x32_bf16 v[90:93], v[206:209], v[172:175], v[90:93]
	v_mfma_f32_16x16x32_bf16 v[102:105], v[198:201], v[180:183], v[102:105]
	v_mfma_f32_16x16x32_bf16 v[82:85], v[206:209], v[180:183], v[82:85]
	v_mfma_f32_16x16x32_bf16 v[98:101], v[198:201], v[190:193], v[98:101]
	v_mfma_f32_16x16x32_bf16 v[86:89], v[206:209], v[190:193], v[86:89]
	s_setprio 0
	s_mov_b32 m0, s95
	v_lshl_add_u64 v[154:155], v[212:213], 0, s[40:41]
	s_barrier
	ds_read_b128 v[146:149], v253 offset:49152
	ds_read_b128 v[150:153], v253 offset:50176
	ds_read_b128 v[168:171], v253 offset:51200
	ds_read_b128 v[172:175], v253 offset:52224
	ds_read_b128 v[176:179], v253 offset:53248
	ds_read_b128 v[180:183], v253 offset:54272
	ds_read_b128 v[184:187], v253 offset:55296
	ds_read_b128 v[190:193], v253 offset:56320
	global_load_lds_dwordx4 v[154:155], off
	v_lshl_add_u64 v[154:155], v[214:215], 0, s[40:41]
	s_mov_b32 m0, s96
	s_nop 0
	global_load_lds_dwordx4 v[154:155], off
	s_barrier
	s_waitcnt lgkmcnt(0)
	s_setprio 1
	s_waitcnt lgkmcnt(0)
	v_mfma_f32_16x16x32_bf16 v[62:65], v[130:133], v[146:149], v[62:65]
	v_mfma_f32_16x16x32_bf16 v[10:13], v[138:141], v[146:149], v[10:13]
	v_mfma_f32_16x16x32_bf16 v[58:61], v[130:133], v[168:171], v[58:61]
	v_mfma_f32_16x16x32_bf16 v[14:17], v[138:141], v[168:171], v[14:17]
	v_mfma_f32_16x16x32_bf16 v[54:57], v[130:133], v[176:179], v[54:57]
	v_mfma_f32_16x16x32_bf16 v[6:9], v[138:141], v[176:179], v[6:9]
	v_mfma_f32_16x16x32_bf16 v[42:45], v[130:133], v[184:187], v[42:45]
	v_mfma_f32_16x16x32_bf16 v[2:5], v[138:141], v[184:187], v[2:5]
	v_mfma_f32_16x16x32_bf16 v[62:65], v[134:137], v[150:153], v[62:65]
	v_mfma_f32_16x16x32_bf16 v[10:13], v[142:145], v[150:153], v[10:13]
	v_mfma_f32_16x16x32_bf16 v[58:61], v[134:137], v[172:175], v[58:61]
	v_mfma_f32_16x16x32_bf16 v[14:17], v[142:145], v[172:175], v[14:17]
	v_mfma_f32_16x16x32_bf16 v[54:57], v[134:137], v[180:183], v[54:57]
	v_mfma_f32_16x16x32_bf16 v[6:9], v[142:145], v[180:183], v[6:9]
	v_mfma_f32_16x16x32_bf16 v[42:45], v[134:137], v[190:193], v[42:45]
	v_mfma_f32_16x16x32_bf16 v[2:5], v[142:145], v[190:193], v[2:5]
	s_setprio 0
	s_barrier
	s_add_u32 s6, s90, 0x40080
	s_addc_u32 s7, s91, 0
	s_add_i32 s90, s92, s39
	v_lshl_add_u64 v[130:131], s[6:7], 0, v[160:161]
	s_mov_b32 m0, s90
	s_nop 0
	global_load_lds_dwordx4 v[130:131], off
	v_lshl_add_u64 v[130:131], s[6:7], 0, v[156:157]
	s_add_i32 m0, s90, 0x2000
	s_nop 0
	global_load_lds_dwordx4 v[130:131], off
	s_waitcnt vmcnt(10)
	s_barrier
	s_setprio 1
	v_mfma_f32_16x16x32_bf16 v[50:53], v[194:197], v[146:149], v[50:53]
	v_mfma_f32_16x16x32_bf16 v[26:29], v[202:205], v[146:149], v[26:29]
	v_mfma_f32_16x16x32_bf16 v[46:49], v[194:197], v[168:171], v[46:49]
	v_mfma_f32_16x16x32_bf16 v[30:33], v[202:205], v[168:171], v[30:33]
	v_mfma_f32_16x16x32_bf16 v[38:41], v[194:197], v[176:179], v[38:41]
	v_mfma_f32_16x16x32_bf16 v[22:25], v[202:205], v[176:179], v[22:25]
	v_mfma_f32_16x16x32_bf16 v[34:37], v[194:197], v[184:187], v[34:37]
	v_mfma_f32_16x16x32_bf16 v[18:21], v[202:205], v[184:187], v[18:21]
	v_mfma_f32_16x16x32_bf16 v[50:53], v[198:201], v[150:153], v[50:53]
	v_mfma_f32_16x16x32_bf16 v[26:29], v[206:209], v[150:153], v[26:29]
	v_mfma_f32_16x16x32_bf16 v[46:49], v[198:201], v[172:175], v[46:49]
	v_mfma_f32_16x16x32_bf16 v[30:33], v[206:209], v[172:175], v[30:33]
	v_mfma_f32_16x16x32_bf16 v[38:41], v[198:201], v[180:183], v[38:41]
	v_mfma_f32_16x16x32_bf16 v[22:25], v[206:209], v[180:183], v[22:25]
	v_mfma_f32_16x16x32_bf16 v[34:37], v[198:201], v[190:193], v[34:37]
	v_mfma_f32_16x16x32_bf16 v[18:21], v[206:209], v[190:193], v[18:21]
	s_setprio 0
	s_add_i32 s45, s45, 2
	s_add_u32 s28, s28, 0x100
	s_addc_u32 s29, s29, 0
	s_cmp_gt_u32 s45, 13
	s_mov_b64 s[6:7], s[88:89]
	s_barrier
	s_cbranch_scc0 .LBB0_919
	v_mov_b32_e32 v131, v252
	s_lshl_b32 s88, s5, 7
	v_bfe_u32 v130, v131, 4, 2
	v_and_b32_e32 v134, 15, v131
	v_lshlrev_b32_e32 v0, 4, v130
	s_ashr_i32 s89, s88, 31
	s_lshl_b32 s15, s4, 8
	v_or3_b32 v135, v0, s97, v134
	s_lshl_b64 s[4:5], s[88:89], 2
	v_lshrrev_b32_e32 v140, 1, v135
	s_add_u32 s4, s73, s4
	s_addc_u32 s5, s74, s5
	v_lshlrev_b32_e32 v0, 2, v140
	v_and_b32_e32 v144, 1, v131
	v_lshl_add_u64 v[132:133], s[4:5], 0, v[0:1]
	v_cmp_eq_u32_e32 vcc, 1, v144
	v_mov_b32_e32 v0, 0xb00
	s_movk_i32 s4, 0x5000
	v_cndmask_b32_e32 v141, 0, v0, vcc
	v_lshlrev_b32_e32 v0, 2, v141
	v_lshl_add_u64 v[132:133], v[132:133], 0, v[0:1]
	v_add_co_u32_e32 v138, vcc, s4, v132
	s_mov_b32 s4, 0xb000
	s_nop 0
	v_addc_co_u32_e32 v139, vcc, 0, v133, vcc
	global_load_dword v136, v[132:133], off
	global_load_dword v137, v[138:139], off offset:2048
	v_add_co_u32_e32 v132, vcc, s4, v132
	v_add_u32_e32 v0, s88, v141
	s_nop 0
	v_addc_co_u32_e32 v133, vcc, 0, v133, vcc
	global_load_dword v138, v[132:133], off
	v_or_b32_e32 v132, v140, v0
	v_ashrrev_i32_e32 v133, 31, v132
	v_lshl_add_u64 v[132:133], v[132:133], 2, s[12:13]
	global_load_dword v139, v[132:133], off
	v_lshl_add_u32 v0, v135, 4, s78
	v_and_b32_e32 v135, 63, v131
	v_cmp_eq_u32_e32 vcc, 0, v144
	s_waitcnt vmcnt(0)
	ds_write_b128 v0, v[136:139]
	v_or_b32_e32 v0, s97, v135
	v_lshrrev_b32_e32 v0, 1, v0
	v_and_or_b32 v131, v0, 63, s55
	v_add_u32_e32 v132, s15, v131
	v_ashrrev_i32_e32 v133, 31, v132
	v_lshlrev_b64 v[132:133], 6, v[132:133]
	v_lshl_add_u64 v[132:133], s[10:11], 0, v[132:133]
	v_lshlrev_b32_e32 v0, 5, v144
	v_lshl_add_u64 v[132:133], v[132:133], 0, v[0:1]
	global_load_dwordx4 v[136:139], v[132:133], off offset:16
	global_load_dwordx4 v[140:143], v[132:133], off
	s_waitcnt vmcnt(0)
	v_add_f32_e32 v133, v138, v139
	v_add_f32_e32 v0, v140, v141
	v_add_f32_e32 v132, v142, v143
	v_add_f32_e32 v0, v0, v132
	v_add_f32_e32 v132, v136, v137
	v_add_f32_e32 v132, v132, v133
	v_add_f32_e32 v0, v0, v132
	v_lshlrev_b32_e32 v132, 2, v135
	v_xor_b32_e32 v132, 4, v132
	ds_bpermute_b32 v132, v132, v0
	s_and_saveexec_b64 s[4:5], vcc
	s_cbranch_execz .LBB0_922
	s_waitcnt lgkmcnt(0)
	v_add_f32_e32 v0, v0, v132
	v_mov_b32_e32 v132, 0x358637bd
	v_fmamk_f32 v0, v0, 0x3a800000, v132
	s_mov_b32 s6, 0x800000
	v_mul_f32_e32 v132, 0x4b800000, v0
	v_cmp_gt_f32_e32 vcc, s6, v0
	v_lshl_add_u32 v131, v131, 2, 0
	v_add_u32_e32 v131, 0x20000, v131
	v_cndmask_b32_e32 v0, v0, v132, vcc
	v_rsq_f32_e32 v0, v0
	s_nop 0
	v_mul_f32_e32 v132, 0x45800000, v0
	v_cndmask_b32_e32 v0, v0, v132, vcc
	ds_write_b32 v131, v0

.LBB0_1090:
	s_add_u32 s84, s16, 0x100
	s_addc_u32 s85, s17, 0
	s_add_i32 s90, 0, 0x10000
	v_add_u32_e32 v142, s90, v212
	ds_read_b128 v[130:133], v142
	ds_read_b128 v[134:137], v142 offset:1024
	ds_read_b128 v[138:141], v142 offset:2048
	ds_read_b128 v[142:145], v142 offset:3072
	s_cmp_eq_u32 s79, 40
	s_cselect_b32 s89, s5, s85
	s_cselect_b32 s88, s4, s84
	s_cselect_b32 s87, s7, s78
	s_cselect_b32 s86, s6, s34
	v_lshl_add_u64 v[178:179], s[16:17], 0, v[196:197]
	s_add_i32 m0, s39, 0xc000
	ds_read_b128 v[146:149], v213
	ds_read_b128 v[150:153], v213 offset:1024
	ds_read_b128 v[154:157], v213 offset:2048
	ds_read_b128 v[158:161], v213 offset:3072
	ds_read_b128 v[162:165], v213 offset:4096
	ds_read_b128 v[166:169], v213 offset:5120
	ds_read_b128 v[170:173], v213 offset:6144
	ds_read_b128 v[174:177], v213 offset:7168
	global_load_lds_dwordx4 v[178:179], off
	v_lshl_add_u64 v[178:179], s[16:17], 0, v[198:199]
	s_add_i32 m0, s39, 0xe000
	s_nop 0
	global_load_lds_dwordx4 v[178:179], off
	s_waitcnt lgkmcnt(8)
	s_waitcnt vmcnt(10)
	s_barrier
	s_waitcnt lgkmcnt(0)
	s_setprio 1
	s_waitcnt lgkmcnt(0)
	v_mfma_f32_16x16x32_bf16 v[126:129], v[130:133], v[146:149], v[126:129]
	v_mfma_f32_16x16x32_bf16 v[122:125], v[138:141], v[146:149], v[122:125]
	v_mfma_f32_16x16x32_bf16 v[110:113], v[130:133], v[154:157], v[110:113]
	v_mfma_f32_16x16x32_bf16 v[106:109], v[138:141], v[154:157], v[106:109]
	v_mfma_f32_16x16x32_bf16 v[94:97], v[130:133], v[162:165], v[94:97]
	v_mfma_f32_16x16x32_bf16 v[90:93], v[138:141], v[162:165], v[90:93]
	v_mfma_f32_16x16x32_bf16 v[78:81], v[130:133], v[170:173], v[78:81]
	v_mfma_f32_16x16x32_bf16 v[74:77], v[138:141], v[170:173], v[74:77]
	v_mfma_f32_16x16x32_bf16 v[126:129], v[134:137], v[150:153], v[126:129]
	v_mfma_f32_16x16x32_bf16 v[122:125], v[142:145], v[150:153], v[122:125]
	v_mfma_f32_16x16x32_bf16 v[110:113], v[134:137], v[158:161], v[110:113]
	v_mfma_f32_16x16x32_bf16 v[106:109], v[142:145], v[158:161], v[106:109]
	v_mfma_f32_16x16x32_bf16 v[94:97], v[134:137], v[166:169], v[94:97]
	v_mfma_f32_16x16x32_bf16 v[90:93], v[142:145], v[166:169], v[90:93]
	v_mfma_f32_16x16x32_bf16 v[78:81], v[134:137], v[174:177], v[78:81]
	v_mfma_f32_16x16x32_bf16 v[74:77], v[142:145], v[174:177], v[74:77]
	s_setprio 0
	s_barrier
	s_add_i32 s91, 0, 0x14000
	v_add_u32_e32 v186, s91, v212
	s_add_i32 s16, s90, s38
	ds_read_b128 v[178:181], v186
	ds_read_b128 v[182:185], v186 offset:1024
	ds_read_b128 v[200:203], v186 offset:2048
	ds_read_b128 v[204:207], v186 offset:3072
	v_lshl_add_u64 v[186:187], s[86:87], 0, v[0:1]
	s_mov_b32 m0, s16
	v_lshl_add_u64 v[208:209], s[86:87], 0, v[194:195]
	global_load_lds_dwordx4 v[186:187], off
	s_add_i32 m0, s16, 0x2000
	s_nop 0
	global_load_lds_dwordx4 v[208:209], off
	s_waitcnt vmcnt(10)
	s_barrier
	s_waitcnt lgkmcnt(0)
	s_setprio 1
	s_waitcnt lgkmcnt(0)
	v_mfma_f32_16x16x32_bf16 v[118:121], v[178:181], v[146:149], v[118:121]
	v_mfma_f32_16x16x32_bf16 v[114:117], v[200:203], v[146:149], v[114:117]
	v_mfma_f32_16x16x32_bf16 v[102:105], v[178:181], v[154:157], v[102:105]
	v_mfma_f32_16x16x32_bf16 v[98:101], v[200:203], v[154:157], v[98:101]
	v_mfma_f32_16x16x32_bf16 v[86:89], v[178:181], v[162:165], v[86:89]
	v_mfma_f32_16x16x32_bf16 v[82:85], v[200:203], v[162:165], v[82:85]
	v_mfma_f32_16x16x32_bf16 v[70:73], v[178:181], v[170:173], v[70:73]
	v_mfma_f32_16x16x32_bf16 v[66:69], v[200:203], v[170:173], v[66:69]
	v_mfma_f32_16x16x32_bf16 v[118:121], v[182:185], v[150:153], v[118:121]
	v_mfma_f32_16x16x32_bf16 v[114:117], v[204:207], v[150:153], v[114:117]
	v_mfma_f32_16x16x32_bf16 v[102:105], v[182:185], v[158:161], v[102:105]
	v_mfma_f32_16x16x32_bf16 v[98:101], v[204:207], v[158:161], v[98:101]
	v_mfma_f32_16x16x32_bf16 v[86:89], v[182:185], v[166:169], v[86:89]
	v_mfma_f32_16x16x32_bf16 v[82:85], v[204:207], v[166:169], v[82:85]
	v_mfma_f32_16x16x32_bf16 v[70:73], v[182:185], v[174:177], v[70:73]
	v_mfma_f32_16x16x32_bf16 v[66:69], v[204:207], v[174:177], v[66:69]
	s_setprio 0
	s_mov_b32 m0, s39
	v_lshl_add_u64 v[210:211], s[88:89], 0, v[190:191]
	s_barrier
	ds_read_b128 v[146:149], v213 offset:16384
	ds_read_b128 v[150:153], v213 offset:17408
	ds_read_b128 v[154:157], v213 offset:18432
	ds_read_b128 v[158:161], v213 offset:19456
	ds_read_b128 v[162:165], v213 offset:20480
	ds_read_b128 v[166:169], v213 offset:21504
	ds_read_b128 v[170:173], v213 offset:22528
	ds_read_b128 v[174:177], v213 offset:23552
	global_load_lds_dwordx4 v[210:211], off
	v_lshl_add_u64 v[214:215], s[88:89], 0, v[192:193]
	s_mov_b32 m0, s42
	s_nop 0
	global_load_lds_dwordx4 v[214:215], off
	s_barrier
	s_waitcnt lgkmcnt(0)
	s_setprio 1
	s_waitcnt lgkmcnt(0)
	v_mfma_f32_16x16x32_bf16 v[62:65], v[130:133], v[146:149], v[62:65]
	v_mfma_f32_16x16x32_bf16 v[58:61], v[138:141], v[146:149], v[58:61]
	v_mfma_f32_16x16x32_bf16 v[46:49], v[130:133], v[154:157], v[46:49]
	v_mfma_f32_16x16x32_bf16 v[42:45], v[138:141], v[154:157], v[42:45]
	v_mfma_f32_16x16x32_bf16 v[30:33], v[130:133], v[162:165], v[30:33]
	v_mfma_f32_16x16x32_bf16 v[26:29], v[138:141], v[162:165], v[26:29]
	v_mfma_f32_16x16x32_bf16 v[14:17], v[130:133], v[170:173], v[14:17]
	v_mfma_f32_16x16x32_bf16 v[10:13], v[138:141], v[170:173], v[10:13]
	v_mfma_f32_16x16x32_bf16 v[62:65], v[134:137], v[150:153], v[62:65]
	v_mfma_f32_16x16x32_bf16 v[58:61], v[142:145], v[150:153], v[58:61]
	v_mfma_f32_16x16x32_bf16 v[46:49], v[134:137], v[158:161], v[46:49]
	v_mfma_f32_16x16x32_bf16 v[42:45], v[142:145], v[158:161], v[42:45]
	v_mfma_f32_16x16x32_bf16 v[30:33], v[134:137], v[166:169], v[30:33]
	v_mfma_f32_16x16x32_bf16 v[26:29], v[142:145], v[166:169], v[26:29]
	v_mfma_f32_16x16x32_bf16 v[14:17], v[134:137], v[174:177], v[14:17]
	v_mfma_f32_16x16x32_bf16 v[10:13], v[142:145], v[174:177], v[10:13]
	s_setprio 0
	s_barrier
	s_add_u32 s16, s86, 0xb0000
	s_addc_u32 s17, s87, 0
	s_add_i32 s90, s91, s38
	v_lshl_add_u64 v[130:131], s[16:17], 0, v[0:1]
	s_mov_b32 m0, s90
	s_nop 0
	global_load_lds_dwordx4 v[130:131], off
	v_lshl_add_u64 v[130:131], s[16:17], 0, v[194:195]
	s_add_i32 m0, s90, 0x2000
	s_nop 0
	global_load_lds_dwordx4 v[130:131], off
	s_waitcnt vmcnt(10)
	s_barrier
	s_setprio 1
	v_mfma_f32_16x16x32_bf16 v[54:57], v[178:181], v[146:149], v[54:57]
	v_mfma_f32_16x16x32_bf16 v[50:53], v[200:203], v[146:149], v[50:53]
	v_mfma_f32_16x16x32_bf16 v[38:41], v[178:181], v[154:157], v[38:41]
	v_mfma_f32_16x16x32_bf16 v[34:37], v[200:203], v[154:157], v[34:37]
	v_mfma_f32_16x16x32_bf16 v[22:25], v[178:181], v[162:165], v[22:25]
	v_mfma_f32_16x16x32_bf16 v[18:21], v[200:203], v[162:165], v[18:21]
	v_mfma_f32_16x16x32_bf16 v[6:9], v[178:181], v[170:173], v[6:9]
	v_mfma_f32_16x16x32_bf16 v[2:5], v[200:203], v[170:173], v[2:5]
	v_mfma_f32_16x16x32_bf16 v[54:57], v[182:185], v[150:153], v[54:57]
	v_mfma_f32_16x16x32_bf16 v[50:53], v[204:207], v[150:153], v[50:53]
	v_mfma_f32_16x16x32_bf16 v[38:41], v[182:185], v[158:161], v[38:41]
	v_mfma_f32_16x16x32_bf16 v[34:37], v[204:207], v[158:161], v[34:37]
	v_mfma_f32_16x16x32_bf16 v[22:25], v[182:185], v[166:169], v[22:25]
	v_mfma_f32_16x16x32_bf16 v[18:21], v[204:207], v[166:169], v[18:21]
	v_mfma_f32_16x16x32_bf16 v[6:9], v[182:185], v[174:177], v[6:9]
	v_mfma_f32_16x16x32_bf16 v[2:5], v[204:207], v[174:177], v[2:5]
	s_setprio 0
	s_add_i32 s90, 0, 0x18000
	v_add_u32_e32 v142, s90, v212
	s_barrier
	ds_read_b128 v[130:133], v142
	ds_read_b128 v[134:137], v142 offset:1024
	ds_read_b128 v[138:141], v142 offset:2048
	ds_read_b128 v[142:145], v142 offset:3072
	s_add_u32 s16, s88, 0xb0000
	s_addc_u32 s17, s89, 0
	s_mov_b32 m0, s43
	v_lshl_add_u64 v[178:179], s[16:17], 0, v[190:191]
	ds_read_b128 v[146:149], v213 offset:32768
	ds_read_b128 v[150:153], v213 offset:33792
	ds_read_b128 v[154:157], v213 offset:34816
	ds_read_b128 v[158:161], v213 offset:35840
	ds_read_b128 v[162:165], v213 offset:36864
	ds_read_b128 v[166:169], v213 offset:37888
	ds_read_b128 v[170:173], v213 offset:38912
	ds_read_b128 v[174:177], v213 offset:39936
	global_load_lds_dwordx4 v[178:179], off
	v_lshl_add_u64 v[178:179], s[16:17], 0, v[192:193]
	s_mov_b32 m0, s44
	s_nop 0
	global_load_lds_dwordx4 v[178:179], off
	s_waitcnt lgkmcnt(8)
	s_waitcnt vmcnt(10)
	s_barrier
	s_waitcnt lgkmcnt(0)
	s_setprio 1
	s_waitcnt lgkmcnt(0)
	v_mfma_f32_16x16x32_bf16 v[126:129], v[130:133], v[146:149], v[126:129]
	v_mfma_f32_16x16x32_bf16 v[122:125], v[138:141], v[146:149], v[122:125]
	v_mfma_f32_16x16x32_bf16 v[110:113], v[130:133], v[154:157], v[110:113]
	v_mfma_f32_16x16x32_bf16 v[106:109], v[138:141], v[154:157], v[106:109]
	v_mfma_f32_16x16x32_bf16 v[94:97], v[130:133], v[162:165], v[94:97]
	v_mfma_f32_16x16x32_bf16 v[90:93], v[138:141], v[162:165], v[90:93]
	v_mfma_f32_16x16x32_bf16 v[78:81], v[130:133], v[170:173], v[78:81]
	v_mfma_f32_16x16x32_bf16 v[74:77], v[138:141], v[170:173], v[74:77]
	v_mfma_f32_16x16x32_bf16 v[126:129], v[134:137], v[150:153], v[126:129]
	v_mfma_f32_16x16x32_bf16 v[122:125], v[142:145], v[150:153], v[122:125]
	v_mfma_f32_16x16x32_bf16 v[110:113], v[134:137], v[158:161], v[110:113]
	v_mfma_f32_16x16x32_bf16 v[106:109], v[142:145], v[158:161], v[106:109]
	v_mfma_f32_16x16x32_bf16 v[94:97], v[134:137], v[166:169], v[94:97]
	v_mfma_f32_16x16x32_bf16 v[90:93], v[142:145], v[166:169], v[90:93]
	v_mfma_f32_16x16x32_bf16 v[78:81], v[134:137], v[174:177], v[78:81]
	v_mfma_f32_16x16x32_bf16 v[74:77], v[142:145], v[174:177], v[74:77]
	s_setprio 0
	s_barrier
	s_add_i32 s88, 0, 0x1c000
	s_add_i32 s16, s90, s38
	v_add_u32_e32 v204, s88, v212
	v_lshl_add_u64 v[186:187], v[186:187], 0, s[40:41]
	s_mov_b32 m0, s16
	ds_read_b128 v[178:181], v204
	ds_read_b128 v[182:185], v204 offset:1024
	ds_read_b128 v[200:203], v204 offset:2048
	ds_read_b128 v[204:207], v204 offset:3072
	global_load_lds_dwordx4 v[186:187], off
	v_lshl_add_u64 v[186:187], v[208:209], 0, s[40:41]
	s_add_i32 m0, s16, 0x2000
	s_nop 0
	global_load_lds_dwordx4 v[186:187], off
	s_waitcnt vmcnt(10)
	s_barrier
	s_waitcnt lgkmcnt(0)
	s_setprio 1
	s_waitcnt lgkmcnt(0)
	v_mfma_f32_16x16x32_bf16 v[118:121], v[178:181], v[146:149], v[118:121]
	v_mfma_f32_16x16x32_bf16 v[114:117], v[200:203], v[146:149], v[114:117]
	v_mfma_f32_16x16x32_bf16 v[102:105], v[178:181], v[154:157], v[102:105]
	v_mfma_f32_16x16x32_bf16 v[98:101], v[200:203], v[154:157], v[98:101]
	v_mfma_f32_16x16x32_bf16 v[86:89], v[178:181], v[162:165], v[86:89]
	v_mfma_f32_16x16x32_bf16 v[82:85], v[200:203], v[162:165], v[82:85]
	v_mfma_f32_16x16x32_bf16 v[70:73], v[178:181], v[170:173], v[70:73]
	v_mfma_f32_16x16x32_bf16 v[66:69], v[200:203], v[170:173], v[66:69]
	v_mfma_f32_16x16x32_bf16 v[118:121], v[182:185], v[150:153], v[118:121]
	v_mfma_f32_16x16x32_bf16 v[114:117], v[204:207], v[150:153], v[114:117]
	v_mfma_f32_16x16x32_bf16 v[102:105], v[182:185], v[158:161], v[102:105]
	v_mfma_f32_16x16x32_bf16 v[98:101], v[204:207], v[158:161], v[98:101]
	v_mfma_f32_16x16x32_bf16 v[86:89], v[182:185], v[166:169], v[86:89]
	v_mfma_f32_16x16x32_bf16 v[82:85], v[204:207], v[166:169], v[82:85]
	v_mfma_f32_16x16x32_bf16 v[70:73], v[182:185], v[174:177], v[70:73]
	v_mfma_f32_16x16x32_bf16 v[66:69], v[204:207], v[174:177], v[66:69]
	s_setprio 0
	s_mov_b32 m0, s60
	v_lshl_add_u64 v[186:187], v[210:211], 0, s[40:41]
	s_barrier
	ds_read_b128 v[146:149], v213 offset:49152
	ds_read_b128 v[150:153], v213 offset:50176
	ds_read_b128 v[154:157], v213 offset:51200
	ds_read_b128 v[158:161], v213 offset:52224
	ds_read_b128 v[162:165], v213 offset:53248
	ds_read_b128 v[166:169], v213 offset:54272
	ds_read_b128 v[170:173], v213 offset:55296
	ds_read_b128 v[174:177], v213 offset:56320
	global_load_lds_dwordx4 v[186:187], off
	v_lshl_add_u64 v[186:187], v[214:215], 0, s[40:41]
	s_mov_b32 m0, s61
	s_nop 0
	global_load_lds_dwordx4 v[186:187], off
	s_barrier
	s_waitcnt lgkmcnt(0)
	s_setprio 1
	s_waitcnt lgkmcnt(0)
	v_mfma_f32_16x16x32_bf16 v[62:65], v[130:133], v[146:149], v[62:65]
	v_mfma_f32_16x16x32_bf16 v[58:61], v[138:141], v[146:149], v[58:61]
	v_mfma_f32_16x16x32_bf16 v[46:49], v[130:133], v[154:157], v[46:49]
	v_mfma_f32_16x16x32_bf16 v[42:45], v[138:141], v[154:157], v[42:45]
	v_mfma_f32_16x16x32_bf16 v[30:33], v[130:133], v[162:165], v[30:33]
	v_mfma_f32_16x16x32_bf16 v[26:29], v[138:141], v[162:165], v[26:29]
	v_mfma_f32_16x16x32_bf16 v[14:17], v[130:133], v[170:173], v[14:17]
	v_mfma_f32_16x16x32_bf16 v[10:13], v[138:141], v[170:173], v[10:13]
	v_mfma_f32_16x16x32_bf16 v[62:65], v[134:137], v[150:153], v[62:65]
	v_mfma_f32_16x16x32_bf16 v[58:61], v[142:145], v[150:153], v[58:61]
	v_mfma_f32_16x16x32_bf16 v[46:49], v[134:137], v[158:161], v[46:49]
	v_mfma_f32_16x16x32_bf16 v[42:45], v[142:145], v[158:161], v[42:45]
	v_mfma_f32_16x16x32_bf16 v[30:33], v[134:137], v[166:169], v[30:33]
	v_mfma_f32_16x16x32_bf16 v[26:29], v[142:145], v[166:169], v[26:29]
	v_mfma_f32_16x16x32_bf16 v[14:17], v[134:137], v[174:177], v[14:17]
	v_mfma_f32_16x16x32_bf16 v[10:13], v[142:145], v[174:177], v[10:13]
	s_setprio 0
	s_barrier
	s_add_u32 s16, s86, 0xb0080
	s_addc_u32 s17, s87, 0
	s_add_i32 s86, s88, s38
	v_lshl_add_u64 v[130:131], s[16:17], 0, v[0:1]
	s_mov_b32 m0, s86
	s_nop 0
	global_load_lds_dwordx4 v[130:131], off
	v_lshl_add_u64 v[130:131], s[16:17], 0, v[194:195]
	s_add_i32 m0, s86, 0x2000
	s_nop 0
	global_load_lds_dwordx4 v[130:131], off
	s_waitcnt vmcnt(10)
	s_barrier
	s_setprio 1
	v_mfma_f32_16x16x32_bf16 v[54:57], v[178:181], v[146:149], v[54:57]
	v_mfma_f32_16x16x32_bf16 v[50:53], v[200:203], v[146:149], v[50:53]
	v_mfma_f32_16x16x32_bf16 v[38:41], v[178:181], v[154:157], v[38:41]
	v_mfma_f32_16x16x32_bf16 v[34:37], v[200:203], v[154:157], v[34:37]
	v_mfma_f32_16x16x32_bf16 v[22:25], v[178:181], v[162:165], v[22:25]
	v_mfma_f32_16x16x32_bf16 v[18:21], v[200:203], v[162:165], v[18:21]
	v_mfma_f32_16x16x32_bf16 v[6:9], v[178:181], v[170:173], v[6:9]
	v_mfma_f32_16x16x32_bf16 v[2:5], v[200:203], v[170:173], v[2:5]
	v_mfma_f32_16x16x32_bf16 v[54:57], v[182:185], v[150:153], v[54:57]
	v_mfma_f32_16x16x32_bf16 v[50:53], v[204:207], v[150:153], v[50:53]
	v_mfma_f32_16x16x32_bf16 v[38:41], v[182:185], v[158:161], v[38:41]
	v_mfma_f32_16x16x32_bf16 v[34:37], v[204:207], v[158:161], v[34:37]
	v_mfma_f32_16x16x32_bf16 v[22:25], v[182:185], v[166:169], v[22:25]
	v_mfma_f32_16x16x32_bf16 v[18:21], v[204:207], v[166:169], v[18:21]
	v_mfma_f32_16x16x32_bf16 v[6:9], v[182:185], v[174:177], v[6:9]
	v_mfma_f32_16x16x32_bf16 v[2:5], v[204:207], v[174:177], v[2:5]
	s_setprio 0
	s_add_i32 s79, s79, 2
	s_add_u32 s34, s34, 0x100
	s_addc_u32 s78, s78, 0
	s_cmp_gt_u32 s79, 41
	s_mov_b64 s[16:17], s[84:85]
	s_barrier
	s_cbranch_scc0 .LBB0_1090
	s_lshl_b32 s16, s23, 8
	v_mov_b32_e32 v186, v252
	s_add_i32 s16, s16, s47
	s_nop 0
	v_and_or_b32 v202, v186, 15, s16
	s_lshl_b32 s16, s22, 8
	s_or_b32 s16, s16, s55
	v_lshrrev_b32_e32 v130, 1, v186
	v_and_or_b32 v200, v130, 24, s16
	v_ashrrev_i32_e32 v201, 31, v200
	v_ashrrev_i32_e32 v203, 31, v202
	v_lshl_add_u64 v[204:205], v[200:201], 2, s[12:13]
	v_lshlrev_b64 v[130:131], 12, v[202:203]
	v_lshl_add_u64 v[130:131], v[204:205], 0, v[130:131]
	global_load_dwordx4 v[216:219], v[130:131], off offset:16
	global_load_dwordx4 v[220:223], v[130:131], off
	global_load_dwordx4 v[178:181], v[130:131], off offset:528
	global_load_dwordx4 v[182:185], v[130:131], off offset:512
	v_or_b32_e32 v210, 16, v202
	v_ashrrev_i32_e32 v211, 31, v210
	v_lshlrev_b64 v[130:131], 12, v[210:211]
	v_or_b32_e32 v208, 32, v202
	v_lshl_add_u64 v[130:131], v[204:205], 0, v[130:131]
	v_ashrrev_i32_e32 v209, 31, v208
	global_load_dwordx4 v[170:173], v[130:131], off offset:16
	global_load_dwordx4 v[174:177], v[130:131], off
	global_load_dwordx4 v[162:165], v[130:131], off offset:528
	global_load_dwordx4 v[166:169], v[130:131], off offset:512
	v_lshlrev_b64 v[130:131], 12, v[208:209]
	v_or_b32_e32 v206, 48, v202
	v_lshl_add_u64 v[130:131], v[204:205], 0, v[130:131]
	v_ashrrev_i32_e32 v207, 31, v206
	global_load_dwordx4 v[154:157], v[130:131], off offset:16
	global_load_dwordx4 v[158:161], v[130:131], off
	global_load_dwordx4 v[138:141], v[130:131], off offset:528
	global_load_dwordx4 v[142:145], v[130:131], off offset:512
	v_lshlrev_b64 v[130:131], 12, v[206:207]
	v_lshl_add_u64 v[134:135], v[204:205], 0, v[130:131]
	global_load_dwordx4 v[146:149], v[134:135], off offset:16
	global_load_dwordx4 v[150:153], v[134:135], off
	global_load_dwordx4 v[130:133], v[134:135], off offset:528
	s_nop 0
	global_load_dwordx4 v[134:137], v[134:135], off offset:512
	v_and_b32_e32 v186, 63, v186
	v_lshlrev_b32_e32 v187, 2, v186
	v_xor_b32_e32 v215, 64, v187
	v_xor_b32_e32 v214, 0x80, v187
	v_cmp_gt_u32_e32 vcc, 16, v186
	v_lshlrev_b64 v[186:187], 10, v[202:203]
	v_lshl_add_u64 v[186:187], v[186:187], 0, v[200:201]
	s_lshl_b32 s16, s22, 2
	s_ashr_i32 s17, s16, 31
	s_waitcnt vmcnt(0)
	v_pk_add_f32 v[124:125], v[124:125], v[218:219]
	v_pk_add_f32 v[128:129], v[128:129], v[222:223]
	v_pk_add_f32 v[126:127], v[126:127], v[220:221]
	v_pk_mul_f32 v[218:219], v[128:129], v[128:129]
	v_pk_mul_f32 v[220:221], v[126:127], v[126:127]
	v_pk_add_f32 v[122:123], v[122:123], v[216:217]
	v_lshl_add_u64 v[216:217], v[186:187], 2, s[14:15]
	v_add_f32_e32 v220, v220, v221
	v_add_f32_e32 v218, v218, v219
	global_store_dwordx4 v[216:217], v[126:129], off
	global_store_dwordx4 v[216:217], v[122:125], off offset:16
	v_add_f32_e32 v222, v220, v218
	v_pk_mul_f32 v[220:221], v[122:123], v[122:123]
	v_cvt_pk_bf16_f32 v126, v126, v127
	v_cvt_pk_bf16_f32 v127, v128, v129
	v_cvt_pk_bf16_f32 v128, v122, v123
	v_cvt_pk_bf16_f32 v129, v124, v125
	v_lshl_add_u64 v[122:123], v[186:187], 1, s[80:81]
	v_pk_add_f32 v[120:121], v[120:121], v[184:185]
	v_pk_add_f32 v[118:119], v[118:119], v[182:183]
	v_pk_mul_f32 v[218:219], v[124:125], v[124:125]
	global_store_dwordx4 v[122:123], v[126:129], off
	v_pk_mul_f32 v[124:125], v[120:121], v[120:121]
	v_pk_add_f32 v[116:117], v[116:117], v[180:181]
	v_pk_mul_f32 v[126:127], v[118:119], v[118:119]
	v_pk_add_f32 v[114:115], v[114:115], v[178:179]
	v_add_f32_e32 v126, v126, v127
	v_add_f32_e32 v124, v124, v125
	v_add_f32_e32 v128, v126, v124
	v_pk_mul_f32 v[124:125], v[116:117], v[116:117]
	v_pk_mul_f32 v[126:127], v[114:115], v[114:115]
	v_add_f32_e32 v220, v220, v221
	v_add_f32_e32 v218, v218, v219
	v_add_f32_e32 v126, v126, v127
	v_add_f32_e32 v124, v124, v125
	v_add_f32_e32 v218, v220, v218
	v_add_f32_e32 v124, v126, v124
	v_add_f32_e32 v218, v222, v218
	v_add_f32_e32 v124, v128, v124
	v_add_f32_e32 v124, v218, v124
	global_store_dwordx4 v[216:217], v[118:121], off offset:512
	global_store_dwordx4 v[216:217], v[114:117], off offset:528
	s_nop 0
	v_cvt_pk_bf16_f32 v118, v118, v119
	v_cvt_pk_bf16_f32 v119, v120, v121
	v_cvt_pk_bf16_f32 v120, v114, v115
	ds_bpermute_b32 v114, v215, v124
	v_cvt_pk_bf16_f32 v121, v116, v117
	global_store_dwordx4 v[122:123], v[118:121], off offset:256
	s_waitcnt lgkmcnt(0)
	v_add_f32_e32 v114, v124, v114
	ds_bpermute_b32 v115, v214, v114
	s_and_saveexec_b64 s[22:23], vcc
	s_cbranch_execz .LBB0_1093
	v_lshlrev_b64 v[116:117], 6, v[202:203]
	v_lshl_add_u64 v[116:117], s[82:83], 0, v[116:117]
	v_lshl_add_u64 v[116:117], s[16:17], 2, v[116:117]
	s_lshl_b32 s34, s45, 2
	v_lshl_add_u64 v[116:117], v[116:117], 0, s[34:35]
	s_waitcnt lgkmcnt(0)
	v_add_f32_e32 v114, v114, v115
	global_store_dword v[116:117], v114, off

.LBB0_1209:
	s_add_u32 s87, s88, 0xfffc0080
	s_addc_u32 s90, s89, -1
	s_add_i32 s94, 0, 0x10000
	s_waitcnt lgkmcnt(0)
	v_add_u32_e32 v0, s94, v170
	ds_read_b128 v[130:133], v0
	ds_read_b128 v[134:137], v0 offset:1024
	ds_read_b128 v[138:141], v0 offset:2048
	ds_read_b128 v[142:145], v0 offset:3072
	s_cmp_eq_u32 s85, 12
	s_cselect_b32 s93, s13, s90
	s_cselect_b32 s92, s22, s87
	s_cselect_b32 s91, s7, s79
	s_cselect_b32 s90, s23, s34
	v_lshl_add_u64 v[194:195], s[88:89], 0, v[154:155]
	s_add_i32 m0, s39, 0xc000
	ds_read_b128 v[158:161], v171
	ds_read_b128 v[162:165], v171 offset:1024
	ds_read_b128 v[166:169], v171 offset:2048
	ds_read_b128 v[172:175], v171 offset:3072
	ds_read_b128 v[176:179], v171 offset:4096
	ds_read_b128 v[180:183], v171 offset:5120
	ds_read_b128 v[184:187], v171 offset:6144
	ds_read_b128 v[190:193], v171 offset:7168
	global_load_lds_dwordx4 v[194:195], off
	v_lshl_add_u64 v[194:195], s[88:89], 0, v[156:157]
	s_add_i32 m0, s39, 0xe000
	s_nop 0
	global_load_lds_dwordx4 v[194:195], off
	s_waitcnt lgkmcnt(8)
	s_waitcnt vmcnt(10)
	s_barrier
	s_waitcnt lgkmcnt(0)
	s_setprio 1
	s_waitcnt lgkmcnt(0)
	v_mfma_f32_16x16x32_bf16 v[126:129], v[130:133], v[158:161], v[126:129]
	v_mfma_f32_16x16x32_bf16 v[122:125], v[138:141], v[158:161], v[122:125]
	v_mfma_f32_16x16x32_bf16 v[110:113], v[130:133], v[166:169], v[110:113]
	v_mfma_f32_16x16x32_bf16 v[106:109], v[138:141], v[166:169], v[106:109]
	v_mfma_f32_16x16x32_bf16 v[94:97], v[130:133], v[176:179], v[94:97]
	v_mfma_f32_16x16x32_bf16 v[90:93], v[138:141], v[176:179], v[90:93]
	v_mfma_f32_16x16x32_bf16 v[78:81], v[130:133], v[184:187], v[78:81]
	v_mfma_f32_16x16x32_bf16 v[74:77], v[138:141], v[184:187], v[74:77]
	v_mfma_f32_16x16x32_bf16 v[126:129], v[134:137], v[162:165], v[126:129]
	v_mfma_f32_16x16x32_bf16 v[122:125], v[142:145], v[162:165], v[122:125]
	v_mfma_f32_16x16x32_bf16 v[110:113], v[134:137], v[172:175], v[110:113]
	v_mfma_f32_16x16x32_bf16 v[106:109], v[142:145], v[172:175], v[106:109]
	v_mfma_f32_16x16x32_bf16 v[94:97], v[134:137], v[180:183], v[94:97]
	v_mfma_f32_16x16x32_bf16 v[90:93], v[142:145], v[180:183], v[90:93]
	v_mfma_f32_16x16x32_bf16 v[78:81], v[134:137], v[190:193], v[78:81]
	v_mfma_f32_16x16x32_bf16 v[74:77], v[142:145], v[190:193], v[74:77]
	s_setprio 0
	s_barrier
	s_add_i32 s87, 0, 0x14000
	s_add_i32 s94, s94, s38
	v_add_u32_e32 v0, s87, v170
	v_lshl_add_u64 v[210:211], s[90:91], 0, v[148:149]
	s_mov_b32 m0, s94
	ds_read_b128 v[194:197], v0
	ds_read_b128 v[198:201], v0 offset:1024
	ds_read_b128 v[202:205], v0 offset:2048
	ds_read_b128 v[206:209], v0 offset:3072
	global_load_lds_dwordx4 v[210:211], off
	v_lshl_add_u64 v[212:213], s[90:91], 0, v[152:153]
	s_add_i32 m0, s94, 0x2000
	s_nop 0
	global_load_lds_dwordx4 v[212:213], off
	s_waitcnt vmcnt(10)
	s_barrier
	s_waitcnt lgkmcnt(0)
	s_setprio 1
	s_waitcnt lgkmcnt(0)
	v_mfma_f32_16x16x32_bf16 v[118:121], v[194:197], v[158:161], v[118:121]
	v_mfma_f32_16x16x32_bf16 v[114:117], v[202:205], v[158:161], v[114:117]
	v_mfma_f32_16x16x32_bf16 v[102:105], v[194:197], v[166:169], v[102:105]
	v_mfma_f32_16x16x32_bf16 v[98:101], v[202:205], v[166:169], v[98:101]
	v_mfma_f32_16x16x32_bf16 v[86:89], v[194:197], v[176:179], v[86:89]
	v_mfma_f32_16x16x32_bf16 v[82:85], v[202:205], v[176:179], v[82:85]
	v_mfma_f32_16x16x32_bf16 v[70:73], v[194:197], v[184:187], v[70:73]
	v_mfma_f32_16x16x32_bf16 v[66:69], v[202:205], v[184:187], v[66:69]
	v_mfma_f32_16x16x32_bf16 v[118:121], v[198:201], v[162:165], v[118:121]
	v_mfma_f32_16x16x32_bf16 v[114:117], v[206:209], v[162:165], v[114:117]
	v_mfma_f32_16x16x32_bf16 v[102:105], v[198:201], v[172:175], v[102:105]
	v_mfma_f32_16x16x32_bf16 v[98:101], v[206:209], v[172:175], v[98:101]
	v_mfma_f32_16x16x32_bf16 v[86:89], v[198:201], v[180:183], v[86:89]
	v_mfma_f32_16x16x32_bf16 v[82:85], v[206:209], v[180:183], v[82:85]
	v_mfma_f32_16x16x32_bf16 v[70:73], v[198:201], v[190:193], v[70:73]
	v_mfma_f32_16x16x32_bf16 v[66:69], v[206:209], v[190:193], v[66:69]
	s_setprio 0
	s_mov_b32 m0, s39
	v_lshl_add_u64 v[214:215], s[92:93], 0, v[146:147]
	s_barrier
	ds_read_b128 v[158:161], v171 offset:16384
	ds_read_b128 v[162:165], v171 offset:17408
	ds_read_b128 v[166:169], v171 offset:18432
	ds_read_b128 v[172:175], v171 offset:19456
	ds_read_b128 v[176:179], v171 offset:20480
	ds_read_b128 v[180:183], v171 offset:21504
	ds_read_b128 v[184:187], v171 offset:22528
	ds_read_b128 v[190:193], v171 offset:23552
	global_load_lds_dwordx4 v[214:215], off
	v_lshl_add_u64 v[216:217], s[92:93], 0, v[150:151]
	s_mov_b32 m0, s42
	s_nop 0
	global_load_lds_dwordx4 v[216:217], off
	s_barrier
	s_waitcnt lgkmcnt(0)
	s_setprio 1
	s_waitcnt lgkmcnt(0)
	v_mfma_f32_16x16x32_bf16 v[62:65], v[130:133], v[158:161], v[62:65]
	v_mfma_f32_16x16x32_bf16 v[58:61], v[138:141], v[158:161], v[58:61]
	v_mfma_f32_16x16x32_bf16 v[46:49], v[130:133], v[166:169], v[46:49]
	v_mfma_f32_16x16x32_bf16 v[42:45], v[138:141], v[166:169], v[42:45]
	v_mfma_f32_16x16x32_bf16 v[30:33], v[130:133], v[176:179], v[30:33]
	v_mfma_f32_16x16x32_bf16 v[26:29], v[138:141], v[176:179], v[26:29]
	v_mfma_f32_16x16x32_bf16 v[14:17], v[130:133], v[184:187], v[14:17]
	v_mfma_f32_16x16x32_bf16 v[10:13], v[138:141], v[184:187], v[10:13]
	v_mfma_f32_16x16x32_bf16 v[62:65], v[134:137], v[162:165], v[62:65]
	v_mfma_f32_16x16x32_bf16 v[58:61], v[142:145], v[162:165], v[58:61]
	v_mfma_f32_16x16x32_bf16 v[46:49], v[134:137], v[172:175], v[46:49]
	v_mfma_f32_16x16x32_bf16 v[42:45], v[142:145], v[172:175], v[42:45]
	v_mfma_f32_16x16x32_bf16 v[30:33], v[134:137], v[180:183], v[30:33]
	v_mfma_f32_16x16x32_bf16 v[26:29], v[142:145], v[180:183], v[26:29]
	v_mfma_f32_16x16x32_bf16 v[14:17], v[134:137], v[190:193], v[14:17]
	v_mfma_f32_16x16x32_bf16 v[10:13], v[142:145], v[190:193], v[10:13]
	s_setprio 0
	s_barrier
	s_add_u32 s94, s90, 0x40000
	s_addc_u32 s95, s91, 0
	s_add_i32 s87, s87, s38
	v_lshl_add_u64 v[130:131], s[94:95], 0, v[148:149]
	s_mov_b32 m0, s87
	s_nop 0
	global_load_lds_dwordx4 v[130:131], off
	v_lshl_add_u64 v[130:131], s[94:95], 0, v[152:153]
	s_add_i32 m0, s87, 0x2000
	s_nop 0
	global_load_lds_dwordx4 v[130:131], off
	s_waitcnt vmcnt(10)
	s_barrier
	s_setprio 1
	v_mfma_f32_16x16x32_bf16 v[54:57], v[194:197], v[158:161], v[54:57]
	v_mfma_f32_16x16x32_bf16 v[50:53], v[202:205], v[158:161], v[50:53]
	v_mfma_f32_16x16x32_bf16 v[38:41], v[194:197], v[166:169], v[38:41]
	v_mfma_f32_16x16x32_bf16 v[34:37], v[202:205], v[166:169], v[34:37]
	v_mfma_f32_16x16x32_bf16 v[22:25], v[194:197], v[176:179], v[22:25]
	v_mfma_f32_16x16x32_bf16 v[18:21], v[202:205], v[176:179], v[18:21]
	v_mfma_f32_16x16x32_bf16 v[6:9], v[194:197], v[184:187], v[6:9]
	v_mfma_f32_16x16x32_bf16 v[2:5], v[202:205], v[184:187], v[2:5]
	v_mfma_f32_16x16x32_bf16 v[54:57], v[198:201], v[162:165], v[54:57]
	v_mfma_f32_16x16x32_bf16 v[50:53], v[206:209], v[162:165], v[50:53]
	v_mfma_f32_16x16x32_bf16 v[38:41], v[198:201], v[172:175], v[38:41]
	v_mfma_f32_16x16x32_bf16 v[34:37], v[206:209], v[172:175], v[34:37]
	v_mfma_f32_16x16x32_bf16 v[22:25], v[198:201], v[180:183], v[22:25]
	v_mfma_f32_16x16x32_bf16 v[18:21], v[206:209], v[180:183], v[18:21]
	v_mfma_f32_16x16x32_bf16 v[6:9], v[198:201], v[190:193], v[6:9]
	v_mfma_f32_16x16x32_bf16 v[2:5], v[206:209], v[190:193], v[2:5]
	s_setprio 0
	s_add_i32 s87, 0, 0x18000
	v_add_u32_e32 v0, s87, v170
	s_barrier
	ds_read_b128 v[130:133], v0
	ds_read_b128 v[134:137], v0 offset:1024
	ds_read_b128 v[138:141], v0 offset:2048
	ds_read_b128 v[142:145], v0 offset:3072
	s_add_u32 s92, s92, 0x40000
	s_addc_u32 s93, s93, 0
	s_mov_b32 m0, s43
	v_lshl_add_u64 v[194:195], s[92:93], 0, v[146:147]
	ds_read_b128 v[158:161], v171 offset:32768
	ds_read_b128 v[162:165], v171 offset:33792
	ds_read_b128 v[166:169], v171 offset:34816
	ds_read_b128 v[172:175], v171 offset:35840
	ds_read_b128 v[176:179], v171 offset:36864
	ds_read_b128 v[180:183], v171 offset:37888
	ds_read_b128 v[184:187], v171 offset:38912
	ds_read_b128 v[190:193], v171 offset:39936
	global_load_lds_dwordx4 v[194:195], off
	v_lshl_add_u64 v[194:195], s[92:93], 0, v[150:151]
	s_mov_b32 m0, s44
	s_nop 0
	global_load_lds_dwordx4 v[194:195], off
	s_waitcnt lgkmcnt(8)
	s_waitcnt vmcnt(10)
	s_barrier
	s_waitcnt lgkmcnt(0)
	s_setprio 1
	s_waitcnt lgkmcnt(0)
	v_mfma_f32_16x16x32_bf16 v[126:129], v[130:133], v[158:161], v[126:129]
	v_mfma_f32_16x16x32_bf16 v[122:125], v[138:141], v[158:161], v[122:125]
	v_mfma_f32_16x16x32_bf16 v[110:113], v[130:133], v[166:169], v[110:113]
	v_mfma_f32_16x16x32_bf16 v[106:109], v[138:141], v[166:169], v[106:109]
	v_mfma_f32_16x16x32_bf16 v[94:97], v[130:133], v[176:179], v[94:97]
	v_mfma_f32_16x16x32_bf16 v[90:93], v[138:141], v[176:179], v[90:93]
	v_mfma_f32_16x16x32_bf16 v[78:81], v[130:133], v[184:187], v[78:81]
	v_mfma_f32_16x16x32_bf16 v[74:77], v[138:141], v[184:187], v[74:77]
	v_mfma_f32_16x16x32_bf16 v[126:129], v[134:137], v[162:165], v[126:129]
	v_mfma_f32_16x16x32_bf16 v[122:125], v[142:145], v[162:165], v[122:125]
	v_mfma_f32_16x16x32_bf16 v[110:113], v[134:137], v[172:175], v[110:113]
	v_mfma_f32_16x16x32_bf16 v[106:109], v[142:145], v[172:175], v[106:109]
	v_mfma_f32_16x16x32_bf16 v[94:97], v[134:137], v[180:183], v[94:97]
	v_mfma_f32_16x16x32_bf16 v[90:93], v[142:145], v[180:183], v[90:93]
	v_mfma_f32_16x16x32_bf16 v[78:81], v[134:137], v[190:193], v[78:81]
	v_mfma_f32_16x16x32_bf16 v[74:77], v[142:145], v[190:193], v[74:77]
	s_setprio 0
	s_barrier
	s_add_i32 s92, 0, 0x1c000
	s_add_i32 s87, s87, s38
	v_add_u32_e32 v0, s92, v170
	v_lshl_add_u64 v[210:211], v[210:211], 0, s[40:41]
	s_mov_b32 m0, s87
	ds_read_b128 v[194:197], v0
	ds_read_b128 v[198:201], v0 offset:1024
	ds_read_b128 v[202:205], v0 offset:2048
	ds_read_b128 v[206:209], v0 offset:3072
	global_load_lds_dwordx4 v[210:211], off
	v_lshl_add_u64 v[210:211], v[212:213], 0, s[40:41]
	s_add_i32 m0, s87, 0x2000
	s_nop 0
	global_load_lds_dwordx4 v[210:211], off
	s_waitcnt vmcnt(10)
	s_barrier
	s_waitcnt lgkmcnt(0)
	s_setprio 1
	s_waitcnt lgkmcnt(0)
	v_mfma_f32_16x16x32_bf16 v[118:121], v[194:197], v[158:161], v[118:121]
	v_mfma_f32_16x16x32_bf16 v[114:117], v[202:205], v[158:161], v[114:117]
	v_mfma_f32_16x16x32_bf16 v[102:105], v[194:197], v[166:169], v[102:105]
	v_mfma_f32_16x16x32_bf16 v[98:101], v[202:205], v[166:169], v[98:101]
	v_mfma_f32_16x16x32_bf16 v[86:89], v[194:197], v[176:179], v[86:89]
	v_mfma_f32_16x16x32_bf16 v[82:85], v[202:205], v[176:179], v[82:85]
	v_mfma_f32_16x16x32_bf16 v[70:73], v[194:197], v[184:187], v[70:73]
	v_mfma_f32_16x16x32_bf16 v[66:69], v[202:205], v[184:187], v[66:69]
	v_mfma_f32_16x16x32_bf16 v[118:121], v[198:201], v[162:165], v[118:121]
	v_mfma_f32_16x16x32_bf16 v[114:117], v[206:209], v[162:165], v[114:117]
	v_mfma_f32_16x16x32_bf16 v[102:105], v[198:201], v[172:175], v[102:105]
	v_mfma_f32_16x16x32_bf16 v[98:101], v[206:209], v[172:175], v[98:101]
	v_mfma_f32_16x16x32_bf16 v[86:89], v[198:201], v[180:183], v[86:89]
	v_mfma_f32_16x16x32_bf16 v[82:85], v[206:209], v[180:183], v[82:85]
	v_mfma_f32_16x16x32_bf16 v[70:73], v[198:201], v[190:193], v[70:73]
	v_mfma_f32_16x16x32_bf16 v[66:69], v[206:209], v[190:193], v[66:69]
	s_setprio 0
	s_mov_b32 m0, s60
	v_lshl_add_u64 v[210:211], v[214:215], 0, s[40:41]
	s_barrier
	ds_read_b128 v[158:161], v171 offset:49152
	ds_read_b128 v[162:165], v171 offset:50176
	ds_read_b128 v[166:169], v171 offset:51200
	ds_read_b128 v[172:175], v171 offset:52224
	ds_read_b128 v[176:179], v171 offset:53248
	ds_read_b128 v[180:183], v171 offset:54272
	ds_read_b128 v[184:187], v171 offset:55296
	ds_read_b128 v[190:193], v171 offset:56320
	global_load_lds_dwordx4 v[210:211], off
	v_lshl_add_u64 v[210:211], v[216:217], 0, s[40:41]
	s_mov_b32 m0, s61
	s_nop 0
	global_load_lds_dwordx4 v[210:211], off
	s_barrier
	s_waitcnt lgkmcnt(0)
	s_setprio 1
	s_waitcnt lgkmcnt(0)
	v_mfma_f32_16x16x32_bf16 v[62:65], v[130:133], v[158:161], v[62:65]
	v_mfma_f32_16x16x32_bf16 v[58:61], v[138:141], v[158:161], v[58:61]
	v_mfma_f32_16x16x32_bf16 v[46:49], v[130:133], v[166:169], v[46:49]
	v_mfma_f32_16x16x32_bf16 v[42:45], v[138:141], v[166:169], v[42:45]
	v_mfma_f32_16x16x32_bf16 v[30:33], v[130:133], v[176:179], v[30:33]
	v_mfma_f32_16x16x32_bf16 v[26:29], v[138:141], v[176:179], v[26:29]
	v_mfma_f32_16x16x32_bf16 v[14:17], v[130:133], v[184:187], v[14:17]
	v_mfma_f32_16x16x32_bf16 v[10:13], v[138:141], v[184:187], v[10:13]
	v_mfma_f32_16x16x32_bf16 v[62:65], v[134:137], v[162:165], v[62:65]
	v_mfma_f32_16x16x32_bf16 v[58:61], v[142:145], v[162:165], v[58:61]
	v_mfma_f32_16x16x32_bf16 v[46:49], v[134:137], v[172:175], v[46:49]
	v_mfma_f32_16x16x32_bf16 v[42:45], v[142:145], v[172:175], v[42:45]
	v_mfma_f32_16x16x32_bf16 v[30:33], v[134:137], v[180:183], v[30:33]
	v_mfma_f32_16x16x32_bf16 v[26:29], v[142:145], v[180:183], v[26:29]
	v_mfma_f32_16x16x32_bf16 v[14:17], v[134:137], v[190:193], v[14:17]
	v_mfma_f32_16x16x32_bf16 v[10:13], v[142:145], v[190:193], v[10:13]
	s_setprio 0
	s_barrier
	s_add_u32 s90, s90, 0x40080
	s_addc_u32 s91, s91, 0
	s_add_i32 s87, s92, s38
	v_lshl_add_u64 v[130:131], s[90:91], 0, v[148:149]
	s_mov_b32 m0, s87
	s_nop 0
	global_load_lds_dwordx4 v[130:131], off
	v_lshl_add_u64 v[130:131], s[90:91], 0, v[152:153]
	s_add_i32 m0, s87, 0x2000
	s_nop 0
	global_load_lds_dwordx4 v[130:131], off
	s_waitcnt vmcnt(10)
	s_barrier
	s_setprio 1
	v_mfma_f32_16x16x32_bf16 v[54:57], v[194:197], v[158:161], v[54:57]
	v_mfma_f32_16x16x32_bf16 v[50:53], v[202:205], v[158:161], v[50:53]
	v_mfma_f32_16x16x32_bf16 v[38:41], v[194:197], v[166:169], v[38:41]
	v_mfma_f32_16x16x32_bf16 v[34:37], v[202:205], v[166:169], v[34:37]
	v_mfma_f32_16x16x32_bf16 v[22:25], v[194:197], v[176:179], v[22:25]
	v_mfma_f32_16x16x32_bf16 v[18:21], v[202:205], v[176:179], v[18:21]
	v_mfma_f32_16x16x32_bf16 v[6:9], v[194:197], v[184:187], v[6:9]
	v_mfma_f32_16x16x32_bf16 v[2:5], v[202:205], v[184:187], v[2:5]
	v_mfma_f32_16x16x32_bf16 v[54:57], v[198:201], v[162:165], v[54:57]
	v_mfma_f32_16x16x32_bf16 v[50:53], v[206:209], v[162:165], v[50:53]
	v_mfma_f32_16x16x32_bf16 v[38:41], v[198:201], v[172:175], v[38:41]
	v_mfma_f32_16x16x32_bf16 v[34:37], v[206:209], v[172:175], v[34:37]
	v_mfma_f32_16x16x32_bf16 v[22:25], v[198:201], v[180:183], v[22:25]
	v_mfma_f32_16x16x32_bf16 v[18:21], v[206:209], v[180:183], v[18:21]
	v_mfma_f32_16x16x32_bf16 v[6:9], v[198:201], v[190:193], v[6:9]
	v_mfma_f32_16x16x32_bf16 v[2:5], v[206:209], v[190:193], v[2:5]
	s_setprio 0
	s_add_i32 s85, s85, 2
	s_add_u32 s88, s88, 0x100
	s_addc_u32 s89, s89, 0
	s_add_u32 s34, s34, 0x100
	s_addc_u32 s79, s79, 0
	s_cmp_gt_u32 s85, 13
	s_barrier
	s_cbranch_scc0 .LBB0_1209
	v_mov_b32_e32 v131, v252
	s_lshl_b32 s7, s86, 8
	v_and_b32_e32 v130, 63, v131
	v_or_b32_e32 v0, s72, v130
	v_lshrrev_b32_e32 v0, 1, v0
	v_and_or_b32 v132, v0, 63, s73
	v_add_u32_e32 v134, s7, v132
	v_ashrrev_i32_e32 v135, 31, v134
	v_and_b32_e32 v142, 1, v131
	v_lshlrev_b64 v[134:135], 6, v[134:135]
	v_lshl_add_u64 v[134:135], s[82:83], 0, v[134:135]
	v_lshlrev_b32_e32 v0, 5, v142
	v_lshl_add_u64 v[138:139], v[134:135], 0, v[0:1]
	global_load_dwordx4 v[134:137], v[138:139], off
	s_nop 0
	global_load_dwordx4 v[138:141], v[138:139], off offset:16
	v_lshlrev_b32_e32 v0, 2, v130
	v_cmp_eq_u32_e32 vcc, 0, v142
	s_waitcnt vmcnt(0)
	v_add_f32_e32 v133, v134, v135
	v_add_f32_e32 v134, v136, v137
	v_add_f32_e32 v135, v138, v139
	v_add_f32_e32 v136, v140, v141
	v_add_f32_e32 v133, v133, v134
	v_add_f32_e32 v134, v135, v136
	v_add_f32_e32 v133, v133, v134
	v_xor_b32_e32 v134, 4, v0
	ds_bpermute_b32 v134, v134, v133
	s_and_saveexec_b64 s[22:23], vcc
	s_cbranch_execz .LBB0_1212
	s_waitcnt lgkmcnt(0)
	v_add_f32_e32 v133, v133, v134
	v_fmamk_f32 v133, v133, 0x3a800000, v224
	s_mov_b32 s13, 0x800000
	v_mul_f32_e32 v134, 0x4b800000, v133
	v_cmp_gt_f32_e32 vcc, s13, v133
	v_lshl_add_u32 v132, v132, 2, 0
	v_add_u32_e32 v132, 0x20000, v132
	v_cndmask_b32_e32 v133, v133, v134, vcc
	v_rsq_f32_e32 v133, v133
	s_nop 0
	v_mul_f32_e32 v134, 0x45800000, v133
	v_cndmask_b32_e32 v133, v133, v134, vcc
	ds_write_b32 v132, v133
